# adds: sw_rows row loads software-pipelined one row ahead; attention: unmasked copy of both score-halves for non-diagonal tiles (no per-key causal compare/select)
# speedup vs baseline: 1.0162x; 1.0021x over previous
; __device__ __forceinline__ void sw_rows(const bf16_t* Bt, int nrows, const float* shift, float* sW, int gw, int NGW, int lane) {
;     float sh[8][16];
; #pragma unroll
;     for (int b = 0; b < 8; ++b)
; #pragma unroll
;         for (int j = 0; j < 2; ++j) { const f32x4 a0 = *(const f32x4*)(shift + (size_t)b * NMOD + j * 512 + 8 * lane), a1 = *(const f32x4*)(shift + (size_t)b * NMOD + j * 512 + 8 * lane + 4);
;             sh[b][8 * j + 0] = a0[0]; sh[b][8 * j + 1] = a0[1]; sh[b][8 * j + 2] = a0[2]; sh[b][8 * j + 3] = a0[3]; sh[b][8 * j + 4] = a1[0]; sh[b][8 * j + 5] = a1[1]; sh[b][8 * j + 6] = a1[2]; sh[b][8 * j + 7] = a1[3]; }
;     for (int row = gw; row < nrows; row += NGW) {
;         const bf16_t* r = Bt + (size_t)row * 1024 + 8 * lane;
;         const u32x4 w0 = *(const u32x4*)r, w1 = *(const u32x4*)(r + 512);
.LBB0_68:
	s_mul_i32 s19, s52, 0x48000
	s_mul_hi_u32 s18, s52, 0x48000
	s_add_u32 s74, s26, s19
	s_addc_u32 s75, s27, s18
	v_cmp_ne_u32_e64 s[18:19], 1, v131
	s_andn2_b64 vcc, exec, s[38:39]
	s_cbranch_vccnz .LBB0_73
	v_lshl_add_u64 v[32:33], s[74:75], 0, v[132:133]
	s_mov_b64 s[20:21], 0x9000
	s_waitcnt vmcnt(1)
	v_lshl_add_u64 v[4:5], v[32:33], 0, s[20:21]
	s_mov_b32 s20, 0x9000
	v_add_co_u32_e32 v8, vcc, s20, v32
	s_mov_b64 s[20:21], 0x9800
	v_lshl_add_u64 v[12:13], v[32:33], 0, s[20:21]
	s_mov_b64 s[20:21], 0x12000
	v_addc_co_u32_e32 v9, vcc, 0, v33, vcc
	s_waitcnt vmcnt(0)
	v_lshl_add_u64 v[20:21], v[32:33], 0, s[20:21]
	s_mov_b32 s20, 0x12000
	v_add_co_u32_e32 v24, vcc, s20, v32
	s_mov_b64 s[20:21], 0x12800
	v_lshl_add_u64 v[28:29], v[32:33], 0, s[20:21]
	s_mov_b64 s[20:21], 0x1b000
	v_addc_co_u32_e32 v25, vcc, 0, v33, vcc
	v_lshl_add_u64 v[34:35], v[32:33], 0, s[20:21]
	s_mov_b32 s20, 0x1b000
	v_add_co_u32_e32 v40, vcc, s20, v32
	s_mov_b64 s[20:21], 0x1b800
	v_lshl_add_u64 v[44:45], v[32:33], 0, s[20:21]
	s_mov_b64 s[20:21], 0x24000
	v_addc_co_u32_e32 v41, vcc, 0, v33, vcc
	v_lshl_add_u64 v[48:49], v[32:33], 0, s[20:21]
	s_mov_b32 s20, 0x24000
	v_add_co_u32_e32 v56, vcc, s20, v32
	s_mov_b64 s[20:21], 0x24800
	v_lshl_add_u64 v[60:61], v[32:33], 0, s[20:21]
	s_mov_b64 s[20:21], 0x2d000
	v_addc_co_u32_e32 v57, vcc, 0, v33, vcc
	v_lshl_add_u64 v[64:65], v[32:33], 0, s[20:21]
	s_mov_b32 s20, 0x2d000
	v_add_co_u32_e32 v72, vcc, s20, v32
	s_mov_b64 s[20:21], 0x2d800
	v_lshl_add_u64 v[76:77], v[32:33], 0, s[20:21]
	s_mov_b64 s[20:21], 0x36000
	v_addc_co_u32_e32 v73, vcc, 0, v33, vcc
	v_lshl_add_u64 v[80:81], v[32:33], 0, s[20:21]
	s_mov_b32 s20, 0x36000
	v_add_co_u32_e32 v88, vcc, s20, v32
	s_mov_b64 s[20:21], 0x36800
	v_lshl_add_u64 v[92:93], v[32:33], 0, s[20:21]
	s_mov_b64 s[20:21], 0x3f000
	v_addc_co_u32_e32 v89, vcc, 0, v33, vcc
	v_lshl_add_u64 v[96:97], v[32:33], 0, s[20:21]
	s_mov_b32 s20, 0x3f000
	v_add_co_u32_e32 v104, vcc, s20, v32
	s_mov_b64 s[20:21], 0x3f800
	s_nop 0
	v_addc_co_u32_e32 v105, vcc, 0, v33, vcc
	v_lshl_add_u64 v[108:109], v[32:33], 0, s[20:21]
	global_load_dwordx4 v[0:3], v[8:9], off
	s_nop 0
	global_load_dwordx4 v[4:7], v[4:5], off offset:16
	s_nop 0
	global_load_dwordx4 v[8:11], v[8:9], off offset:2048
	s_nop 0
	global_load_dwordx4 v[12:15], v[12:13], off offset:16
	s_nop 0
	global_load_dwordx4 v[16:19], v[24:25], off
	s_nop 0
	global_load_dwordx4 v[20:23], v[20:21], off offset:16
	s_nop 0
	global_load_dwordx4 v[24:27], v[24:25], off offset:2048
	s_nop 0
	global_load_dwordx4 v[28:31], v[28:29], off offset:16
	s_nop 0
	global_load_dwordx4 v[32:35], v[34:35], off offset:16
	s_nop 0
	global_load_dwordx4 v[36:39], v[40:41], off
	s_nop 0
	global_load_dwordx4 v[40:43], v[40:41], off offset:2048
	s_nop 0
	global_load_dwordx4 v[44:47], v[44:45], off offset:16
	s_nop 0
	global_load_dwordx4 v[48:51], v[48:49], off offset:16
	s_nop 0
	global_load_dwordx4 v[52:55], v[56:57], off
	s_nop 0
	global_load_dwordx4 v[56:59], v[56:57], off offset:2048
	s_nop 0
	global_load_dwordx4 v[60:63], v[60:61], off offset:16
	s_nop 0
	global_load_dwordx4 v[64:67], v[64:65], off offset:16
	s_nop 0
	global_load_dwordx4 v[68:71], v[72:73], off
	s_nop 0
	global_load_dwordx4 v[72:75], v[72:73], off offset:2048
	s_nop 0
	global_load_dwordx4 v[76:79], v[76:77], off offset:16
	s_nop 0
	global_load_dwordx4 v[80:83], v[80:81], off offset:16
	s_nop 0
	global_load_dwordx4 v[84:87], v[88:89], off
	s_nop 0
	global_load_dwordx4 v[88:91], v[88:89], off offset:2048
	s_nop 0
	global_load_dwordx4 v[92:95], v[92:93], off offset:16
	s_nop 0
	global_load_dwordx4 v[96:99], v[96:97], off offset:16
	s_nop 0
	global_load_dwordx4 v[100:103], v[104:105], off
	s_nop 0
	global_load_dwordx4 v[104:107], v[104:105], off offset:2048
	s_nop 0
	global_load_dwordx4 v[108:111], v[108:109], off offset:16
	s_nop 0
	global_load_dwordx4 v[112:115], v132, s[74:75]
	global_load_dwordx4 v[116:119], v132, s[74:75] offset:16
	global_load_dwordx4 v[120:123], v132, s[74:75] offset:2048
	global_load_dwordx4 v[124:127], v132, s[74:75] offset:2064
	s_mov_b32 s37, s36
	v_mov_b64_e32 v[152:153], v[138:139]
	global_load_dwordx4 v[230:233], v[152:153], off
	global_load_dwordx4 v[234:237], v[152:153], off offset:1024
	s_waitcnt vmcnt(0)
	v_mov_b64_e32 v[154:155], v[136:137]
	s_branch .LBB0_71

; __device__ __forceinline__ void sw_rows(const bf16_t* Bt, int nrows, const float* shift, float* sW, int gw, int NGW, int lane) {
;     ...
;     for (int row = gw; row < nrows; row += NGW) {
;         const bf16_t* r = Bt + (size_t)row * 1024 + 8 * lane;
;         const u32x4 w0 = *(const u32x4*)r, w1 = *(const u32x4*)(r + 512);
;         float w[16];
;         w[0] = bf_lo(w0.x); w[1] = bf_hi(w0.x); w[2] = bf_lo(w0.y); w[3] = bf_hi(w0.y); w[4] = bf_lo(w0.z); w[5] = bf_hi(w0.z); w[6] = bf_lo(w0.w); w[7] = bf_hi(w0.w);
;         w[8] = bf_lo(w1.x); w[9] = bf_hi(w1.x); w[10] = bf_lo(w1.y); w[11] = bf_hi(w1.y); w[12] = bf_lo(w1.z); w[13] = bf_hi(w1.z); w[14] = bf_lo(w1.w); w[15] = bf_hi(w1.w);
;         float v = 0.f;
; #pragma unroll
;         for (int b = 0; b < 8; ++b) { float acc = 0.f;
; #pragma unroll
;             for (int i = 0; i < 16; ++i) acc += sh[b][i] * w[i];
;             acc = wave_sum(acc); v = (lane == b) ? acc : v; }
.LBB0_71:
	s_waitcnt vmcnt(1) lgkmcnt(0)
	v_mov_b32_e32 v156, v230
	v_mov_b32_e32 v157, v231
	v_mov_b32_e32 v158, v232
	v_mov_b32_e32 v159, v233
	v_mov_b32_e32 v160, v234
	v_mov_b32_e32 v161, v235
	v_mov_b32_e32 v162, v236
	v_mov_b32_e32 v163, v237
	v_lshl_add_u64 v[238:239], v[152:153], 0, s[54:55]
	global_load_dwordx4 v[230:233], v[238:239], off
	global_load_dwordx4 v[234:237], v[238:239], off offset:1024
	v_lshlrev_b32_e32 v166, 16, v156
	s_waitcnt lgkmcnt(2)
	v_and_b32_e32 v167, 0xffff0000, v156
	v_lshlrev_b32_e32 v168, 16, v157
	s_waitcnt lgkmcnt(1)
	v_and_b32_e32 v169, 0xffff0000, v157
	v_fma_f32 v157, v0, v166, 0
	v_fmac_f32_e32 v157, v1, v167
	v_fmac_f32_e32 v157, v2, v168
	v_lshlrev_b32_e32 v170, 16, v158
	v_fmac_f32_e32 v157, v3, v169
	s_waitcnt lgkmcnt(0)
	v_and_b32_e32 v171, 0xffff0000, v158
	v_fmac_f32_e32 v157, v4, v170
	v_lshlrev_b32_e32 v172, 16, v159
	v_fmac_f32_e32 v157, v5, v171
	v_and_b32_e32 v173, 0xffff0000, v159
	v_fmac_f32_e32 v157, v6, v172
	v_lshlrev_b32_e32 v174, 16, v160
	v_fmac_f32_e32 v157, v7, v173
	v_and_b32_e32 v175, 0xffff0000, v160
	v_fmac_f32_e32 v157, v8, v174
	v_lshlrev_b32_e32 v176, 16, v161
	v_fmac_f32_e32 v157, v9, v175
	v_and_b32_e32 v177, 0xffff0000, v161
	v_fmac_f32_e32 v157, v10, v176
	v_lshlrev_b32_e32 v178, 16, v162
	v_fmac_f32_e32 v157, v11, v177
	v_and_b32_e32 v179, 0xffff0000, v162
	v_fmac_f32_e32 v157, v12, v178
	v_lshlrev_b32_e32 v180, 16, v163
	v_fmac_f32_e32 v157, v13, v179
	v_and_b32_e32 v181, 0xffff0000, v163
	v_fmac_f32_e32 v157, v14, v180
	v_fmac_f32_e32 v157, v15, v181
	ds_bpermute_b32 v162, v189, v157
	v_fma_f32 v159, v36, v166, 0
	v_fma_f32 v160, v52, v166, 0
	v_fmac_f32_e32 v159, v37, v167
	v_fmac_f32_e32 v160, v53, v167
	v_fmac_f32_e32 v159, v38, v168
	v_fmac_f32_e32 v160, v54, v168
	v_fmac_f32_e32 v159, v39, v169
	v_fmac_f32_e32 v160, v55, v169
	v_fmac_f32_e32 v159, v32, v170
	v_fmac_f32_e32 v160, v48, v170
	s_waitcnt lgkmcnt(0)
	v_add_f32_e32 v157, v157, v162
	v_fmac_f32_e32 v159, v33, v171
	v_fmac_f32_e32 v160, v49, v171
	ds_bpermute_b32 v162, v190, v157
	v_fmac_f32_e32 v159, v34, v172
	v_fmac_f32_e32 v160, v50, v172
	v_fmac_f32_e32 v159, v35, v173
	v_fmac_f32_e32 v160, v51, v173
	v_fmac_f32_e32 v159, v40, v174
	v_fmac_f32_e32 v160, v56, v174
	v_fmac_f32_e32 v159, v41, v175
	v_fmac_f32_e32 v160, v57, v175
	v_fmac_f32_e32 v159, v42, v176
	v_fmac_f32_e32 v160, v58, v176
	s_waitcnt lgkmcnt(0)
	v_add_f32_e32 v157, v157, v162
	v_fmac_f32_e32 v159, v43, v177
	v_fmac_f32_e32 v160, v59, v177
	ds_bpermute_b32 v162, v191, v157
	v_fmac_f32_e32 v159, v44, v178
	v_fmac_f32_e32 v160, v60, v178
	v_fmac_f32_e32 v159, v45, v179
	v_fmac_f32_e32 v160, v61, v179
	v_fmac_f32_e32 v159, v46, v180
	v_fmac_f32_e32 v160, v62, v180
	v_fmac_f32_e32 v159, v47, v181
	v_fmac_f32_e32 v160, v63, v181
	ds_bpermute_b32 v164, v189, v159
	s_waitcnt lgkmcnt(1)
	v_add_f32_e32 v157, v157, v162
	ds_bpermute_b32 v165, v189, v160
	ds_bpermute_b32 v162, v192, v157
	v_fma_f32 v156, v112, v166, 0
	s_waitcnt lgkmcnt(2)
	v_add_f32_e32 v164, v159, v164
	v_fmac_f32_e32 v156, v113, v167
	s_waitcnt lgkmcnt(1)
	v_add_f32_e32 v160, v160, v165
	s_waitcnt lgkmcnt(0)
	v_add_f32_e32 v157, v157, v162
	ds_bpermute_b32 v162, v190, v164
	ds_bpermute_b32 v165, v190, v160
	v_fmac_f32_e32 v156, v114, v168
	v_fmac_f32_e32 v156, v115, v169
	v_fmac_f32_e32 v156, v116, v170
	s_waitcnt lgkmcnt(1)
	v_add_f32_e32 v162, v164, v162
	s_waitcnt lgkmcnt(0)
	v_add_f32_e32 v160, v160, v165
	ds_bpermute_b32 v164, v191, v162
	ds_bpermute_b32 v165, v191, v160
	v_fmac_f32_e32 v156, v117, v171
	v_fmac_f32_e32 v156, v118, v172
	v_fmac_f32_e32 v156, v119, v173
	s_waitcnt lgkmcnt(1)
	v_add_f32_e32 v162, v162, v164
	s_waitcnt lgkmcnt(0)
	v_add_f32_e32 v160, v160, v165
	ds_bpermute_b32 v164, v192, v162
	ds_bpermute_b32 v165, v192, v160
	v_fmac_f32_e32 v156, v120, v174
	v_fmac_f32_e32 v156, v121, v175
	v_fmac_f32_e32 v156, v122, v176
	v_fmac_f32_e32 v156, v123, v177
	s_waitcnt lgkmcnt(1)
	v_add_f32_e32 v162, v162, v164
	s_waitcnt lgkmcnt(0)
	v_add_f32_e32 v165, v160, v165
	v_fmac_f32_e32 v156, v124, v178
	ds_bpermute_b32 v164, v193, v162
	ds_bpermute_b32 v182, v193, v165
	v_fmac_f32_e32 v156, v125, v179
	v_fmac_f32_e32 v156, v126, v180
	v_fmac_f32_e32 v156, v127, v181
	ds_bpermute_b32 v161, v189, v156
	v_fma_f32 v158, v16, v166, 0
	s_waitcnt lgkmcnt(2)
	v_add_f32_e32 v162, v162, v164
	s_waitcnt lgkmcnt(1)
	v_add_f32_e32 v164, v165, v182
	v_fma_f32 v182, v68, v166, 0
	v_fma_f32 v183, v84, v166, 0
	v_fma_f32 v166, v100, v166, 0
	v_fmac_f32_e32 v158, v17, v167
	v_fmac_f32_e32 v182, v69, v167
	v_fmac_f32_e32 v183, v85, v167
	v_fmac_f32_e32 v166, v101, v167
	v_fmac_f32_e32 v158, v18, v168
	v_fmac_f32_e32 v182, v70, v168
	v_fmac_f32_e32 v183, v86, v168
	v_fmac_f32_e32 v166, v102, v168
	v_fmac_f32_e32 v158, v19, v169
	v_fmac_f32_e32 v182, v71, v169
	v_fmac_f32_e32 v183, v87, v169
	v_fmac_f32_e32 v166, v103, v169
	v_fmac_f32_e32 v158, v20, v170
	s_waitcnt lgkmcnt(0)
	v_add_f32_e32 v156, v156, v161
	v_fmac_f32_e32 v182, v64, v170
	v_fmac_f32_e32 v183, v80, v170
	v_fmac_f32_e32 v166, v96, v170
	v_fmac_f32_e32 v158, v21, v171
	ds_bpermute_b32 v161, v190, v156
	v_fmac_f32_e32 v182, v65, v171
	v_fmac_f32_e32 v183, v81, v171
	v_fmac_f32_e32 v166, v97, v171
	v_fmac_f32_e32 v158, v22, v172
	v_fmac_f32_e32 v182, v66, v172
	v_fmac_f32_e32 v183, v82, v172
	v_fmac_f32_e32 v166, v98, v172
	v_fmac_f32_e32 v158, v23, v173
	v_fmac_f32_e32 v182, v67, v173
	v_fmac_f32_e32 v183, v83, v173
	v_fmac_f32_e32 v166, v99, v173
	v_fmac_f32_e32 v158, v24, v174
	v_fmac_f32_e32 v182, v72, v174
	v_fmac_f32_e32 v183, v88, v174
	v_fmac_f32_e32 v166, v104, v174
	v_fmac_f32_e32 v158, v25, v175
	v_fmac_f32_e32 v182, v73, v175
	v_fmac_f32_e32 v183, v89, v175
	v_fmac_f32_e32 v166, v105, v175
	v_fmac_f32_e32 v158, v26, v176
	s_waitcnt lgkmcnt(0)
; __device__ __forceinline__ void sw_rows(const bf16_t* Bt, int nrows, const float* shift, float* sW, int gw, int NGW, int lane) {
;     ...
;         float v = 0.f;
; #pragma unroll
;         for (int b = 0; b < 8; ++b) { float acc = 0.f;
; #pragma unroll
;             for (int i = 0; i < 16; ++i) acc += sh[b][i] * w[i];
;             acc = wave_sum(acc); v = (lane == b) ? acc : v; }
;         if (lane < 8) sW[(size_t)lane * SW_ROWS + row] = v;
	v_add_f32_e32 v156, v156, v161
	v_fmac_f32_e32 v182, v74, v176
	v_fmac_f32_e32 v183, v90, v176
	v_fmac_f32_e32 v166, v106, v176
	v_fmac_f32_e32 v158, v27, v177
	ds_bpermute_b32 v161, v191, v156
	v_fmac_f32_e32 v182, v75, v177
	v_fmac_f32_e32 v183, v91, v177
	v_fmac_f32_e32 v166, v107, v177
	v_fmac_f32_e32 v158, v28, v178
	v_fmac_f32_e32 v182, v76, v178
	v_fmac_f32_e32 v183, v92, v178
	v_fmac_f32_e32 v166, v108, v178
	v_fmac_f32_e32 v158, v29, v179
	v_fmac_f32_e32 v182, v77, v179
	v_fmac_f32_e32 v183, v93, v179
	v_fmac_f32_e32 v166, v109, v179
	v_fmac_f32_e32 v158, v30, v180
	v_fmac_f32_e32 v182, v78, v180
	v_fmac_f32_e32 v183, v94, v180
	v_fmac_f32_e32 v166, v110, v180
	v_fmac_f32_e32 v158, v31, v181
	v_fmac_f32_e32 v182, v79, v181
	v_fmac_f32_e32 v183, v95, v181
	v_fmac_f32_e32 v166, v111, v181
	ds_bpermute_b32 v163, v189, v158
	s_waitcnt lgkmcnt(1)
	v_add_f32_e32 v156, v156, v161
	ds_bpermute_b32 v167, v189, v182
	ds_bpermute_b32 v168, v189, v183
	ds_bpermute_b32 v169, v189, v166
	ds_bpermute_b32 v161, v192, v156
	s_waitcnt lgkmcnt(4)
	v_add_f32_e32 v163, v158, v163
	s_waitcnt lgkmcnt(3)
	v_add_f32_e32 v167, v182, v167
	s_waitcnt lgkmcnt(2)
	v_add_f32_e32 v168, v183, v168
	s_waitcnt lgkmcnt(1)
	v_add_f32_e32 v166, v166, v169
	s_waitcnt lgkmcnt(0)
	v_add_f32_e32 v156, v156, v161
	ds_bpermute_b32 v161, v190, v163
	ds_bpermute_b32 v170, v190, v167
	ds_bpermute_b32 v171, v190, v168
	ds_bpermute_b32 v169, v190, v166
	ds_bpermute_b32 v158, v193, v156
	s_waitcnt lgkmcnt(4)
	v_add_f32_e32 v161, v163, v161
	s_waitcnt lgkmcnt(3)
	v_add_f32_e32 v167, v167, v170
	s_waitcnt lgkmcnt(2)
	v_add_f32_e32 v168, v168, v171
	s_waitcnt lgkmcnt(1)
	v_add_f32_e32 v166, v166, v169
	ds_bpermute_b32 v163, v191, v161
	ds_bpermute_b32 v170, v191, v167
	ds_bpermute_b32 v171, v191, v168
	ds_bpermute_b32 v169, v191, v166
	ds_bpermute_b32 v159, v193, v157
	s_waitcnt lgkmcnt(4)
	v_add_f32_e32 v161, v161, v163
	s_waitcnt lgkmcnt(3)
	v_add_f32_e32 v167, v167, v170
	s_waitcnt lgkmcnt(2)
	v_add_f32_e32 v168, v168, v171
	s_waitcnt lgkmcnt(1)
	v_add_f32_e32 v166, v166, v169
	ds_bpermute_b32 v163, v192, v161
	ds_bpermute_b32 v170, v192, v167
	ds_bpermute_b32 v171, v192, v168
	ds_bpermute_b32 v169, v192, v166
	v_add_f32_e32 v156, v156, v158
	s_waitcnt lgkmcnt(3)
	v_add_f32_e32 v161, v161, v163
	s_waitcnt lgkmcnt(2)
	v_add_f32_e32 v167, v167, v170
	s_waitcnt lgkmcnt(1)
	v_add_f32_e32 v168, v168, v171
	s_waitcnt lgkmcnt(0)
	v_add_f32_e32 v172, v166, v169
	ds_bpermute_b32 v163, v193, v161
	ds_bpermute_b32 v170, v193, v167
	ds_bpermute_b32 v171, v193, v168
	ds_bpermute_b32 v173, v193, v172
	v_add_f32_e32 v158, v157, v159
	s_waitcnt lgkmcnt(3)
	v_add_f32_e32 v160, v161, v163
	s_waitcnt lgkmcnt(2)
	v_add_f32_e32 v166, v167, v170
	s_waitcnt lgkmcnt(1)
	v_add_f32_e32 v168, v168, v171
	s_waitcnt lgkmcnt(0)
	v_add_f32_e32 v170, v172, v173
	ds_bpermute_b32 v157, v194, v156
	ds_bpermute_b32 v159, v194, v158
	ds_bpermute_b32 v161, v194, v160
	ds_bpermute_b32 v163, v194, v162
	ds_bpermute_b32 v165, v194, v164
	ds_bpermute_b32 v167, v194, v166
	ds_bpermute_b32 v169, v194, v168
	ds_bpermute_b32 v171, v194, v170
	s_and_saveexec_b64 s[20:21], s[22:23]
	s_cbranch_execz .LBB0_70
	s_waitcnt lgkmcnt(7)
	v_add_f32_e32 v156, v156, v157
	s_waitcnt lgkmcnt(6)
	v_add_f32_e32 v158, v158, v159
	v_cndmask_b32_e64 v156, 0, v156, s[0:1]
	s_waitcnt lgkmcnt(5)
	v_add_f32_e32 v160, v160, v161
	v_cndmask_b32_e64 v156, v156, v158, s[16:17]
	s_waitcnt lgkmcnt(4)
	v_add_f32_e32 v162, v162, v163
	v_cndmask_b32_e64 v156, v156, v160, s[14:15]
	s_waitcnt lgkmcnt(3)
	v_add_f32_e32 v164, v164, v165
	v_cndmask_b32_e64 v156, v156, v162, s[12:13]
	s_waitcnt lgkmcnt(2)
	v_add_f32_e32 v166, v166, v167
	v_cndmask_b32_e64 v156, v156, v164, s[10:11]
	s_waitcnt lgkmcnt(1)
	v_add_f32_e32 v168, v168, v169
	v_cndmask_b32_e64 v156, v156, v166, s[8:9]
	s_waitcnt lgkmcnt(0)
	v_add_f32_e32 v170, v170, v171
	v_cndmask_b32_e64 v156, v156, v168, s[6:7]
	v_cndmask_b32_e64 v156, v156, v170, s[4:5]
	global_store_dword v[154:155], v156, off
	s_branch .LBB0_70
; __device__ __forceinline__ void sw_rows(const bf16_t* Bt, int nrows, const float* shift, float* sW, int gw, int NGW, int lane) {
;     float sh[8][16];
; #pragma unroll
;     for (int b = 0; b < 8; ++b)
; #pragma unroll
;         for (int j = 0; j < 2; ++j) { const f32x4 a0 = *(const f32x4*)(shift + (size_t)b * NMOD + j * 512 + 8 * lane), a1 = *(const f32x4*)(shift + (size_t)b * NMOD + j * 512 + 8 * lane + 4);
;             sh[b][8 * j + 0] = a0[0]; sh[b][8 * j + 1] = a0[1]; sh[b][8 * j + 2] = a0[2]; sh[b][8 * j + 3] = a0[3]; sh[b][8 * j + 4] = a1[0]; sh[b][8 * j + 5] = a1[1]; sh[b][8 * j + 6] = a1[2]; sh[b][8 * j + 7] = a1[3]; }
;     for (int row = gw; row < nrows; row += NGW) {
;         const bf16_t* r = Bt + (size_t)row * 1024 + 8 * lane;
;         const u32x4 w0 = *(const u32x4*)r, w1 = *(const u32x4*)(r + 512);
.LBB0_73:
	v_lshl_add_u64 v[24:25], s[74:75], 0, v[132:133]
	s_mov_b64 s[20:21], 0x27000
	v_lshl_add_u64 v[176:177], v[24:25], 0, s[20:21]
	s_mov_b64 s[20:21], 0x27800
	s_waitcnt vmcnt(1)
	v_add_co_u32_e32 v4, vcc, 0x27000, v24
	v_lshl_add_u64 v[178:179], v[24:25], 0, s[20:21]
	s_mov_b64 s[20:21], 0x30000
	v_addc_co_u32_e32 v5, vcc, 0, v25, vcc
	v_lshl_add_u64 v[180:181], v[24:25], 0, s[20:21]
	s_mov_b32 s20, 0x30000
	v_add_co_u32_e32 v6, vcc, s20, v24
	global_load_dwordx4 v[0:3], v[176:177], off offset:16
	global_load_dwordx4 v[8:11], v[178:179], off offset:16
	v_addc_co_u32_e32 v7, vcc, 0, v25, vcc
	global_load_dwordx4 v[12:15], v[4:5], off offset:2048
	global_load_dwordx4 v[16:19], v[6:7], off
	s_nop 0
	global_load_dwordx4 v[4:7], v[4:5], off
	s_nop 0
	global_load_dwordx4 v[20:23], v[180:181], off offset:16
	s_mov_b64 s[20:21], 0x3000
	v_lshl_add_u64 v[152:153], v[24:25], 0, s[20:21]
	s_mov_b64 s[20:21], 0xc000
	v_lshl_add_u64 v[154:155], v[24:25], 0, s[20:21]
	s_mov_b64 s[20:21], 0xc800
	s_waitcnt lgkmcnt(7)
	v_lshl_add_u64 v[156:157], v[24:25], 0, s[20:21]
	s_mov_b64 s[20:21], 0x15000
	s_waitcnt lgkmcnt(6)
	v_lshl_add_u64 v[158:159], v[24:25], 0, s[20:21]
	s_mov_b64 s[20:21], 0x15800
	s_waitcnt lgkmcnt(5)
	v_lshl_add_u64 v[160:161], v[24:25], 0, s[20:21]
	s_mov_b64 s[20:21], 0x1e000
	s_waitcnt lgkmcnt(4)
	v_lshl_add_u64 v[162:163], v[24:25], 0, s[20:21]
	s_mov_b64 s[20:21], 0x1e800
	s_waitcnt lgkmcnt(3)
	v_lshl_add_u64 v[164:165], v[24:25], 0, s[20:21]
	s_mov_b64 s[20:21], 0x30800
	s_waitcnt lgkmcnt(2)
	v_lshl_add_u64 v[166:167], v[24:25], 0, s[20:21]
	s_mov_b64 s[20:21], 0x39000
	s_waitcnt lgkmcnt(1)
	v_lshl_add_u64 v[168:169], v[24:25], 0, s[20:21]
	s_mov_b64 s[20:21], 0x39800
	s_waitcnt lgkmcnt(0)
	v_lshl_add_u64 v[170:171], v[24:25], 0, s[20:21]
	s_mov_b64 s[20:21], 0x42000
	v_cndmask_b32_e64 v26, 0, 1, s[44:45]
	s_mov_b64 s[56:57], 0x42800
	v_lshl_add_u64 v[172:173], v[24:25], 0, s[20:21]
	v_cmp_ne_u32_e64 s[20:21], 1, v26
	s_andn2_b64 vcc, exec, s[44:45]
	v_lshl_add_u64 v[174:175], v[24:25], 0, s[56:57]
	s_cbranch_vccnz .LBB0_79
	global_load_dwordx4 v[24:27], v[152:153], off
	global_load_dwordx4 v[28:31], v[152:153], off offset:16
	global_load_dwordx4 v[32:35], v[152:153], off offset:2048
	global_load_dwordx4 v[36:39], v[152:153], off offset:2064
	global_load_dwordx4 v[40:43], v[154:155], off
	global_load_dwordx4 v[44:47], v[154:155], off offset:16
	global_load_dwordx4 v[48:51], v[156:157], off
	global_load_dwordx4 v[52:55], v[156:157], off offset:16
	global_load_dwordx4 v[56:59], v[158:159], off
	global_load_dwordx4 v[60:63], v[158:159], off offset:16
	global_load_dwordx4 v[64:67], v[160:161], off
	global_load_dwordx4 v[68:71], v[160:161], off offset:16
	global_load_dwordx4 v[72:75], v[162:163], off
	global_load_dwordx4 v[76:79], v[162:163], off offset:16
	global_load_dwordx4 v[80:83], v[164:165], off
	global_load_dwordx4 v[84:87], v[164:165], off offset:16
	global_load_dwordx4 v[88:91], v[166:167], off
	global_load_dwordx4 v[92:95], v[166:167], off offset:16
	global_load_dwordx4 v[96:99], v[168:169], off
	global_load_dwordx4 v[100:103], v[168:169], off offset:16
	global_load_dwordx4 v[104:107], v[170:171], off
	global_load_dwordx4 v[108:111], v[170:171], off offset:16
	global_load_dwordx4 v[112:115], v[172:173], off
	global_load_dwordx4 v[116:119], v[172:173], off offset:16
	global_load_dwordx4 v[120:123], v[174:175], off
	global_load_dwordx4 v[124:127], v[174:175], off offset:16
	v_mov_b64_e32 v[182:183], v[142:143]
	global_load_dwordx4 v[230:233], v[182:183], off
	global_load_dwordx4 v[234:237], v[182:183], off offset:1024
	s_waitcnt vmcnt(0)
	v_mov_b64_e32 v[184:185], v[140:141]
	s_mov_b32 s37, s36
	s_branch .LBB0_76

; __device__ __forceinline__ void sw_rows(const bf16_t* Bt, int nrows, const float* shift, float* sW, int gw, int NGW, int lane) {
;     ...
;     for (int row = gw; row < nrows; row += NGW) {
;         const bf16_t* r = Bt + (size_t)row * 1024 + 8 * lane;
;         const u32x4 w0 = *(const u32x4*)r, w1 = *(const u32x4*)(r + 512);
;         float w[16];
;         w[0] = bf_lo(w0.x); w[1] = bf_hi(w0.x); w[2] = bf_lo(w0.y); w[3] = bf_hi(w0.y); w[4] = bf_lo(w0.z); w[5] = bf_hi(w0.z); w[6] = bf_lo(w0.w); w[7] = bf_hi(w0.w);
;         w[8] = bf_lo(w1.x); w[9] = bf_hi(w1.x); w[10] = bf_lo(w1.y); w[11] = bf_hi(w1.y); w[12] = bf_lo(w1.z); w[13] = bf_hi(w1.z); w[14] = bf_lo(w1.w); w[15] = bf_hi(w1.w);
;         float v = 0.f;
; #pragma unroll
;         for (int b = 0; b < 8; ++b) { float acc = 0.f;
; #pragma unroll
;             for (int i = 0; i < 16; ++i) acc += sh[b][i] * w[i];
;             acc = wave_sum(acc); v = (lane == b) ? acc : v; }
.LBB0_76:
	s_waitcnt vmcnt(1) lgkmcnt(0)
	v_mov_b32_e32 v196, v230
	v_mov_b32_e32 v197, v231
	v_mov_b32_e32 v198, v232
	v_mov_b32_e32 v199, v233
	v_mov_b32_e32 v200, v234
	v_mov_b32_e32 v201, v235
	v_mov_b32_e32 v202, v236
	v_mov_b32_e32 v203, v237
	v_lshl_add_u64 v[238:239], v[182:183], 0, s[54:55]
	global_load_dwordx4 v[230:233], v[238:239], off
	global_load_dwordx4 v[234:237], v[238:239], off offset:1024
	v_lshlrev_b32_e32 v205, 16, v196
	s_waitcnt lgkmcnt(2)
	v_and_b32_e32 v206, 0xffff0000, v196
	v_fma_f32 v196, v40, v205, 0
	v_lshlrev_b32_e32 v207, 16, v197
	v_fmac_f32_e32 v196, v41, v206
	s_waitcnt lgkmcnt(1)
	v_and_b32_e32 v208, 0xffff0000, v197
	v_fmac_f32_e32 v196, v42, v207
	v_lshlrev_b32_e32 v209, 16, v198
	v_fmac_f32_e32 v196, v43, v208
	s_waitcnt lgkmcnt(0)
	v_and_b32_e32 v210, 0xffff0000, v198
	v_fmac_f32_e32 v196, v44, v209
	v_lshlrev_b32_e32 v211, 16, v199
	v_fmac_f32_e32 v196, v45, v210
	v_and_b32_e32 v212, 0xffff0000, v199
	v_fmac_f32_e32 v196, v46, v211
	v_lshlrev_b32_e32 v213, 16, v200
	v_fmac_f32_e32 v196, v47, v212
	v_and_b32_e32 v214, 0xffff0000, v200
	v_fmac_f32_e32 v196, v48, v213
	v_lshlrev_b32_e32 v215, 16, v201
	v_fmac_f32_e32 v196, v49, v214
	v_and_b32_e32 v216, 0xffff0000, v201
	v_fmac_f32_e32 v196, v50, v215
	v_lshlrev_b32_e32 v217, 16, v202
	v_fmac_f32_e32 v196, v51, v216
	v_and_b32_e32 v218, 0xffff0000, v202
	v_fmac_f32_e32 v196, v52, v217
	v_lshlrev_b32_e32 v219, 16, v203
	v_fmac_f32_e32 v196, v53, v218
	v_and_b32_e32 v220, 0xffff0000, v203
	v_fmac_f32_e32 v196, v54, v219
	v_fmac_f32_e32 v196, v55, v220
	ds_bpermute_b32 v201, v189, v196
	v_fma_f32 v198, v72, v205, 0
	v_fma_f32 v199, v4, v205, 0
	v_fmac_f32_e32 v198, v73, v206
	v_fmac_f32_e32 v199, v5, v206
	v_fmac_f32_e32 v198, v74, v207
	v_fmac_f32_e32 v199, v6, v207
	v_fmac_f32_e32 v198, v75, v208
	v_fmac_f32_e32 v199, v7, v208
	v_fmac_f32_e32 v198, v76, v209
	v_fmac_f32_e32 v199, v0, v209
	s_waitcnt lgkmcnt(0)
	v_add_f32_e32 v196, v196, v201
	v_fmac_f32_e32 v198, v77, v210
	v_fmac_f32_e32 v199, v1, v210
	ds_bpermute_b32 v201, v190, v196
	v_fmac_f32_e32 v198, v78, v211
	v_fmac_f32_e32 v199, v2, v211
	v_fmac_f32_e32 v198, v79, v212
	v_fmac_f32_e32 v199, v3, v212
	v_fmac_f32_e32 v198, v80, v213
	v_fmac_f32_e32 v199, v12, v213
	v_fmac_f32_e32 v198, v81, v214
	v_fmac_f32_e32 v199, v13, v214
	v_fmac_f32_e32 v198, v82, v215
	v_fmac_f32_e32 v199, v14, v215
	s_waitcnt lgkmcnt(0)
	v_add_f32_e32 v196, v196, v201
	v_fmac_f32_e32 v198, v83, v216
	v_fmac_f32_e32 v199, v15, v216
	ds_bpermute_b32 v201, v191, v196
	v_fmac_f32_e32 v198, v84, v217
	v_fmac_f32_e32 v199, v8, v217
	v_fmac_f32_e32 v198, v85, v218
	v_fmac_f32_e32 v199, v9, v218
	v_fmac_f32_e32 v198, v86, v219
	v_fmac_f32_e32 v199, v10, v219
	v_fmac_f32_e32 v198, v87, v220
	v_fmac_f32_e32 v199, v11, v220
	ds_bpermute_b32 v203, v189, v198
	s_waitcnt lgkmcnt(1)
	v_add_f32_e32 v196, v196, v201
	ds_bpermute_b32 v204, v189, v199
	ds_bpermute_b32 v201, v192, v196
	v_fma_f32 v195, v24, v205, 0
	s_waitcnt lgkmcnt(2)
	v_add_f32_e32 v203, v198, v203
	v_fmac_f32_e32 v195, v25, v206
	s_waitcnt lgkmcnt(1)
	v_add_f32_e32 v199, v199, v204
	s_waitcnt lgkmcnt(0)
	v_add_f32_e32 v196, v196, v201
	ds_bpermute_b32 v201, v190, v203
	ds_bpermute_b32 v204, v190, v199
	v_fmac_f32_e32 v195, v26, v207
	v_fmac_f32_e32 v195, v27, v208
	v_fmac_f32_e32 v195, v28, v209
	s_waitcnt lgkmcnt(1)
	v_add_f32_e32 v201, v203, v201
	s_waitcnt lgkmcnt(0)
	v_add_f32_e32 v199, v199, v204
	ds_bpermute_b32 v203, v191, v201
	ds_bpermute_b32 v204, v191, v199
	v_fmac_f32_e32 v195, v29, v210
	v_fmac_f32_e32 v195, v30, v211
	v_fmac_f32_e32 v195, v31, v212
	s_waitcnt lgkmcnt(1)
	v_add_f32_e32 v201, v201, v203
	s_waitcnt lgkmcnt(0)
	v_add_f32_e32 v199, v199, v204
	ds_bpermute_b32 v203, v192, v201
	ds_bpermute_b32 v204, v192, v199
	v_fmac_f32_e32 v195, v32, v213
	v_fmac_f32_e32 v195, v33, v214
	v_fmac_f32_e32 v195, v34, v215
	v_fmac_f32_e32 v195, v35, v216
	s_waitcnt lgkmcnt(1)
	v_add_f32_e32 v201, v201, v203
	s_waitcnt lgkmcnt(0)
	v_add_f32_e32 v204, v199, v204
	v_fmac_f32_e32 v195, v36, v217
	ds_bpermute_b32 v203, v193, v201
	ds_bpermute_b32 v221, v193, v204
	v_fmac_f32_e32 v195, v37, v218
	v_fmac_f32_e32 v195, v38, v219
	v_fmac_f32_e32 v195, v39, v220
	ds_bpermute_b32 v200, v189, v195
	v_fma_f32 v197, v56, v205, 0
	s_waitcnt lgkmcnt(2)
	v_add_f32_e32 v201, v201, v203
	s_waitcnt lgkmcnt(1)
	v_add_f32_e32 v203, v204, v221
	v_fma_f32 v221, v16, v205, 0
	v_fma_f32 v223, v96, v205, 0
	v_fma_f32 v205, v112, v205, 0
	v_fmac_f32_e32 v197, v57, v206
	v_fmac_f32_e32 v221, v17, v206
	v_fmac_f32_e32 v223, v97, v206
	v_fmac_f32_e32 v205, v113, v206
	v_fmac_f32_e32 v197, v58, v207
	v_fmac_f32_e32 v221, v18, v207
	v_fmac_f32_e32 v223, v98, v207
	v_fmac_f32_e32 v205, v114, v207
	v_fmac_f32_e32 v197, v59, v208
	v_fmac_f32_e32 v221, v19, v208
	v_fmac_f32_e32 v223, v99, v208
	v_fmac_f32_e32 v205, v115, v208
	v_fmac_f32_e32 v197, v60, v209
	s_waitcnt lgkmcnt(0)
; __device__ __forceinline__ float wave_sum(float v) {
; #pragma unroll
;     for (int o = 1; o < 64; o <<= 1) v += __shfl_xor(v, o);
;     return v;
; }
; __device__ __forceinline__ void sw_rows(const bf16_t* Bt, int nrows, const float* shift, float* sW, int gw, int NGW, int lane) {
;     ...
;         float v = 0.f;
; #pragma unroll
;         for (int b = 0; b < 8; ++b) { float acc = 0.f;
; #pragma unroll
;             for (int i = 0; i < 16; ++i) acc += sh[b][i] * w[i];
;             acc = wave_sum(acc); v = (lane == b) ? acc : v; }
;         if (lane < 8) sW[(size_t)lane * SW_ROWS + row] = v;
	v_add_f32_e32 v195, v195, v200
	v_fmac_f32_e32 v221, v20, v209
	v_fmac_f32_e32 v223, v100, v209
	v_fmac_f32_e32 v205, v116, v209
	v_fmac_f32_e32 v197, v61, v210
	ds_bpermute_b32 v200, v190, v195
	v_fmac_f32_e32 v221, v21, v210
	v_fmac_f32_e32 v223, v101, v210
	v_fmac_f32_e32 v205, v117, v210
	v_fmac_f32_e32 v197, v62, v211
	v_fmac_f32_e32 v221, v22, v211
	v_fmac_f32_e32 v223, v102, v211
	v_fmac_f32_e32 v205, v118, v211
	v_fmac_f32_e32 v197, v63, v212
	v_fmac_f32_e32 v221, v23, v212
	v_fmac_f32_e32 v223, v103, v212
	v_fmac_f32_e32 v205, v119, v212
	v_fmac_f32_e32 v197, v64, v213
	v_fmac_f32_e32 v221, v88, v213
	v_fmac_f32_e32 v223, v104, v213
	v_fmac_f32_e32 v205, v120, v213
	v_fmac_f32_e32 v197, v65, v214
	v_fmac_f32_e32 v221, v89, v214
	v_fmac_f32_e32 v223, v105, v214
	v_fmac_f32_e32 v205, v121, v214
	v_fmac_f32_e32 v197, v66, v215
	s_waitcnt lgkmcnt(0)
	v_add_f32_e32 v195, v195, v200
	v_fmac_f32_e32 v221, v90, v215
	v_fmac_f32_e32 v223, v106, v215
	v_fmac_f32_e32 v205, v122, v215
	v_fmac_f32_e32 v197, v67, v216
	ds_bpermute_b32 v200, v191, v195
	v_fmac_f32_e32 v221, v91, v216
	v_fmac_f32_e32 v223, v107, v216
	v_fmac_f32_e32 v205, v123, v216
	v_fmac_f32_e32 v197, v68, v217
	v_fmac_f32_e32 v221, v92, v217
	v_fmac_f32_e32 v223, v108, v217
	v_fmac_f32_e32 v205, v124, v217
	v_fmac_f32_e32 v197, v69, v218
	v_fmac_f32_e32 v221, v93, v218
	v_fmac_f32_e32 v223, v109, v218
	v_fmac_f32_e32 v205, v125, v218
	v_fmac_f32_e32 v197, v70, v219
	v_fmac_f32_e32 v221, v94, v219
	v_fmac_f32_e32 v223, v110, v219
	v_fmac_f32_e32 v205, v126, v219
	v_fmac_f32_e32 v197, v71, v220
	v_fmac_f32_e32 v221, v95, v220
	v_fmac_f32_e32 v223, v111, v220
	v_fmac_f32_e32 v205, v127, v220
	ds_bpermute_b32 v202, v189, v197
	s_waitcnt lgkmcnt(1)
	v_add_f32_e32 v195, v195, v200
	ds_bpermute_b32 v222, v189, v221
	ds_bpermute_b32 v224, v189, v223
	ds_bpermute_b32 v206, v189, v205
	ds_bpermute_b32 v200, v192, v195
	s_waitcnt lgkmcnt(4)
	v_add_f32_e32 v202, v197, v202
	s_waitcnt lgkmcnt(3)
	v_add_f32_e32 v207, v221, v222
	s_waitcnt lgkmcnt(2)
	v_add_f32_e32 v209, v223, v224
	s_waitcnt lgkmcnt(1)
	v_add_f32_e32 v205, v205, v206
	s_waitcnt lgkmcnt(0)
	v_add_f32_e32 v195, v195, v200
	ds_bpermute_b32 v200, v190, v202
	ds_bpermute_b32 v208, v190, v207
	ds_bpermute_b32 v210, v190, v209
	ds_bpermute_b32 v206, v190, v205
	ds_bpermute_b32 v197, v193, v195
	s_waitcnt lgkmcnt(4)
	v_add_f32_e32 v200, v202, v200
	s_waitcnt lgkmcnt(3)
	v_add_f32_e32 v207, v207, v208
	s_waitcnt lgkmcnt(2)
	v_add_f32_e32 v209, v209, v210
	s_waitcnt lgkmcnt(1)
	v_add_f32_e32 v205, v205, v206
	ds_bpermute_b32 v202, v191, v200
	ds_bpermute_b32 v208, v191, v207
	ds_bpermute_b32 v210, v191, v209
	ds_bpermute_b32 v206, v191, v205
	ds_bpermute_b32 v198, v193, v196
	s_waitcnt lgkmcnt(4)
	v_add_f32_e32 v200, v200, v202
	s_waitcnt lgkmcnt(3)
	v_add_f32_e32 v207, v207, v208
	s_waitcnt lgkmcnt(2)
	v_add_f32_e32 v209, v209, v210
	s_waitcnt lgkmcnt(1)
	v_add_f32_e32 v205, v205, v206
	ds_bpermute_b32 v202, v192, v200
	ds_bpermute_b32 v208, v192, v207
	ds_bpermute_b32 v210, v192, v209
	ds_bpermute_b32 v206, v192, v205
	v_add_f32_e32 v195, v195, v197
	s_waitcnt lgkmcnt(3)
	v_add_f32_e32 v200, v200, v202
	s_waitcnt lgkmcnt(2)
	v_add_f32_e32 v207, v207, v208
	s_waitcnt lgkmcnt(1)
	v_add_f32_e32 v209, v209, v210
	s_waitcnt lgkmcnt(0)
	v_add_f32_e32 v211, v205, v206
	ds_bpermute_b32 v202, v193, v200
	ds_bpermute_b32 v208, v193, v207
	ds_bpermute_b32 v210, v193, v209
	ds_bpermute_b32 v212, v193, v211
	v_add_f32_e32 v197, v196, v198
	s_waitcnt lgkmcnt(3)
	v_add_f32_e32 v199, v200, v202
	s_waitcnt lgkmcnt(2)
	v_add_f32_e32 v205, v207, v208
	s_waitcnt lgkmcnt(1)
	v_add_f32_e32 v207, v209, v210
	s_waitcnt lgkmcnt(0)
	v_add_f32_e32 v209, v211, v212
	ds_bpermute_b32 v196, v194, v195
	ds_bpermute_b32 v198, v194, v197
	ds_bpermute_b32 v200, v194, v199
	ds_bpermute_b32 v202, v194, v201
	ds_bpermute_b32 v204, v194, v203
	ds_bpermute_b32 v206, v194, v205
	ds_bpermute_b32 v208, v194, v207
	ds_bpermute_b32 v210, v194, v209
	s_and_saveexec_b64 s[78:79], s[22:23]
	s_cbranch_execz .LBB0_75
	s_waitcnt lgkmcnt(7)
	v_add_f32_e32 v195, v195, v196
	s_waitcnt lgkmcnt(6)
	v_add_f32_e32 v197, v197, v198
	v_cndmask_b32_e64 v195, 0, v195, s[0:1]
	s_waitcnt lgkmcnt(5)
	v_add_f32_e32 v199, v199, v200
	v_cndmask_b32_e64 v195, v195, v197, s[16:17]
	s_waitcnt lgkmcnt(4)
	v_add_f32_e32 v201, v201, v202
	v_cndmask_b32_e64 v195, v195, v199, s[14:15]
	s_waitcnt lgkmcnt(3)
	v_add_f32_e32 v203, v203, v204
	v_cndmask_b32_e64 v195, v195, v201, s[12:13]
	s_waitcnt lgkmcnt(2)
	v_add_f32_e32 v205, v205, v206
	v_cndmask_b32_e64 v195, v195, v203, s[10:11]
	s_waitcnt lgkmcnt(1)
	v_add_f32_e32 v207, v207, v208
	v_cndmask_b32_e64 v195, v195, v205, s[8:9]
	s_waitcnt lgkmcnt(0)
	v_add_f32_e32 v209, v209, v210
	v_cndmask_b32_e64 v195, v195, v207, s[6:7]
	v_cndmask_b32_e64 v195, v195, v209, s[4:5]
	global_store_dword v[184:185], v195, off
	s_branch .LBB0_75

; __device__ __forceinline__ void sw_rows(const bf16_t* Bt, int nrows, const float* shift, float* sW, int gw, int NGW, int lane) {
;     ...
;     for (int b = 0; b < 8; ++b)
; #pragma unroll
;         for (int j = 0; j < 2; ++j) { const f32x4 a0 = *(const f32x4*)(shift + (size_t)b * NMOD + j * 512 + 8 * lane), a1 = *(const f32x4*)(shift + (size_t)b * NMOD + j * 512 + 8 * lane + 4);
;             sh[b][8 * j + 0] = a0[0]; sh[b][8 * j + 1] = a0[1]; sh[b][8 * j + 2] = a0[2]; sh[b][8 * j + 3] = a0[3]; sh[b][8 * j + 4] = a1[0]; sh[b][8 * j + 5] = a1[1]; sh[b][8 * j + 6] = a1[2]; sh[b][8 * j + 7] = a1[3]; }
;     for (int row = gw; row < nrows; row += NGW) {
;         const bf16_t* r = Bt + (size_t)row * 1024 + 8 * lane;
;         const u32x4 w0 = *(const u32x4*)r, w1 = *(const u32x4*)(r + 512);
.LBB0_79:
	s_andn2_b64 vcc, exec, s[48:49]
	s_cbranch_vccnz .LBB0_84
	global_load_dwordx4 v[24:27], v[152:153], off
	global_load_dwordx4 v[28:31], v[152:153], off offset:16
	global_load_dwordx4 v[32:35], v[152:153], off offset:2048
	global_load_dwordx4 v[36:39], v[152:153], off offset:2064
	global_load_dwordx4 v[40:43], v[154:155], off
	global_load_dwordx4 v[44:47], v[154:155], off offset:16
	global_load_dwordx4 v[48:51], v[156:157], off
	global_load_dwordx4 v[52:55], v[156:157], off offset:16
	global_load_dwordx4 v[56:59], v[158:159], off
	global_load_dwordx4 v[60:63], v[158:159], off offset:16
	global_load_dwordx4 v[64:67], v[160:161], off
	global_load_dwordx4 v[68:71], v[160:161], off offset:16
	global_load_dwordx4 v[72:75], v[162:163], off
	global_load_dwordx4 v[76:79], v[162:163], off offset:16
	global_load_dwordx4 v[80:83], v[164:165], off
	global_load_dwordx4 v[84:87], v[164:165], off offset:16
	global_load_dwordx4 v[88:91], v[166:167], off
	global_load_dwordx4 v[92:95], v[166:167], off offset:16
	global_load_dwordx4 v[96:99], v[168:169], off
	global_load_dwordx4 v[100:103], v[168:169], off offset:16
	global_load_dwordx4 v[104:107], v[170:171], off
	global_load_dwordx4 v[108:111], v[170:171], off offset:16
	global_load_dwordx4 v[112:115], v[172:173], off
	global_load_dwordx4 v[116:119], v[172:173], off offset:16
	global_load_dwordx4 v[120:123], v[174:175], off
	global_load_dwordx4 v[124:127], v[174:175], off offset:16
	v_mov_b64_e32 v[152:153], v[146:147]
	global_load_dwordx4 v[230:233], v[152:153], off
	global_load_dwordx4 v[234:237], v[152:153], off offset:1024
	s_waitcnt vmcnt(0)
	v_mov_b64_e32 v[154:155], v[144:145]
	s_mov_b32 s37, s36
	s_branch .LBB0_82

; __device__ __forceinline__ void sw_rows(const bf16_t* Bt, int nrows, const float* shift, float* sW, int gw, int NGW, int lane) {
;     ...
;     for (int row = gw; row < nrows; row += NGW) {
;         const bf16_t* r = Bt + (size_t)row * 1024 + 8 * lane;
;         const u32x4 w0 = *(const u32x4*)r, w1 = *(const u32x4*)(r + 512);
;         float w[16];
;         w[0] = bf_lo(w0.x); w[1] = bf_hi(w0.x); w[2] = bf_lo(w0.y); w[3] = bf_hi(w0.y); w[4] = bf_lo(w0.z); w[5] = bf_hi(w0.z); w[6] = bf_lo(w0.w); w[7] = bf_hi(w0.w);
;         w[8] = bf_lo(w1.x); w[9] = bf_hi(w1.x); w[10] = bf_lo(w1.y); w[11] = bf_hi(w1.y); w[12] = bf_lo(w1.z); w[13] = bf_hi(w1.z); w[14] = bf_lo(w1.w); w[15] = bf_hi(w1.w);
;         float v = 0.f;
; #pragma unroll
;         for (int b = 0; b < 8; ++b) { float acc = 0.f;
; #pragma unroll
;             for (int i = 0; i < 16; ++i) acc += sh[b][i] * w[i];
;             acc = wave_sum(acc); v = (lane == b) ? acc : v; }
.LBB0_82:
	s_waitcnt vmcnt(1) lgkmcnt(0)
	v_mov_b32_e32 v156, v230
	v_mov_b32_e32 v157, v231
	v_mov_b32_e32 v158, v232
	v_mov_b32_e32 v159, v233
	v_mov_b32_e32 v160, v234
	v_mov_b32_e32 v161, v235
	v_mov_b32_e32 v162, v236
	v_mov_b32_e32 v163, v237
	v_lshl_add_u64 v[238:239], v[152:153], 0, s[54:55]
	global_load_dwordx4 v[230:233], v[238:239], off
	global_load_dwordx4 v[234:237], v[238:239], off offset:1024
	v_lshlrev_b32_e32 v166, 16, v156
	s_waitcnt lgkmcnt(2)
	v_and_b32_e32 v167, 0xffff0000, v156
	v_lshlrev_b32_e32 v168, 16, v157
	s_waitcnt lgkmcnt(1)
	v_and_b32_e32 v169, 0xffff0000, v157
	v_fma_f32 v157, v40, v166, 0
	v_fmac_f32_e32 v157, v41, v167
	v_fmac_f32_e32 v157, v42, v168
	v_lshlrev_b32_e32 v170, 16, v158
	v_fmac_f32_e32 v157, v43, v169
	s_waitcnt lgkmcnt(0)
	v_and_b32_e32 v171, 0xffff0000, v158
	v_fmac_f32_e32 v157, v44, v170
	v_lshlrev_b32_e32 v172, 16, v159
	v_fmac_f32_e32 v157, v45, v171
	v_and_b32_e32 v173, 0xffff0000, v159
	v_fmac_f32_e32 v157, v46, v172
	v_lshlrev_b32_e32 v174, 16, v160
	v_fmac_f32_e32 v157, v47, v173
	v_and_b32_e32 v175, 0xffff0000, v160
	v_fmac_f32_e32 v157, v48, v174
	v_lshlrev_b32_e32 v176, 16, v161
	v_fmac_f32_e32 v157, v49, v175
	v_and_b32_e32 v177, 0xffff0000, v161
	v_fmac_f32_e32 v157, v50, v176
	v_lshlrev_b32_e32 v178, 16, v162
	v_fmac_f32_e32 v157, v51, v177
	v_and_b32_e32 v179, 0xffff0000, v162
	v_fmac_f32_e32 v157, v52, v178
	v_lshlrev_b32_e32 v180, 16, v163
	v_fmac_f32_e32 v157, v53, v179
	v_and_b32_e32 v181, 0xffff0000, v163
	v_fmac_f32_e32 v157, v54, v180
	v_fmac_f32_e32 v157, v55, v181
	ds_bpermute_b32 v162, v189, v157
	v_fma_f32 v159, v72, v166, 0
	v_fma_f32 v160, v4, v166, 0
	v_fmac_f32_e32 v159, v73, v167
	v_fmac_f32_e32 v160, v5, v167
	v_fmac_f32_e32 v159, v74, v168
	v_fmac_f32_e32 v160, v6, v168
	v_fmac_f32_e32 v159, v75, v169
	v_fmac_f32_e32 v160, v7, v169
	v_fmac_f32_e32 v159, v76, v170
	v_fmac_f32_e32 v160, v0, v170
	s_waitcnt lgkmcnt(0)
	v_add_f32_e32 v157, v157, v162
	v_fmac_f32_e32 v159, v77, v171
	v_fmac_f32_e32 v160, v1, v171
	ds_bpermute_b32 v162, v190, v157
	v_fmac_f32_e32 v159, v78, v172
	v_fmac_f32_e32 v160, v2, v172
	v_fmac_f32_e32 v159, v79, v173
	v_fmac_f32_e32 v160, v3, v173
	v_fmac_f32_e32 v159, v80, v174
	v_fmac_f32_e32 v160, v12, v174
	v_fmac_f32_e32 v159, v81, v175
	v_fmac_f32_e32 v160, v13, v175
	v_fmac_f32_e32 v159, v82, v176
	v_fmac_f32_e32 v160, v14, v176
	s_waitcnt lgkmcnt(0)
	v_add_f32_e32 v157, v157, v162
	v_fmac_f32_e32 v159, v83, v177
	v_fmac_f32_e32 v160, v15, v177
	ds_bpermute_b32 v162, v191, v157
	v_fmac_f32_e32 v159, v84, v178
	v_fmac_f32_e32 v160, v8, v178
	v_fmac_f32_e32 v159, v85, v179
	v_fmac_f32_e32 v160, v9, v179
	v_fmac_f32_e32 v159, v86, v180
	v_fmac_f32_e32 v160, v10, v180
	v_fmac_f32_e32 v159, v87, v181
	v_fmac_f32_e32 v160, v11, v181
	ds_bpermute_b32 v164, v189, v159
	s_waitcnt lgkmcnt(1)
	v_add_f32_e32 v157, v157, v162
	ds_bpermute_b32 v165, v189, v160
	ds_bpermute_b32 v162, v192, v157
	v_fma_f32 v156, v24, v166, 0
	s_waitcnt lgkmcnt(2)
	v_add_f32_e32 v164, v159, v164
	v_fmac_f32_e32 v156, v25, v167
	s_waitcnt lgkmcnt(1)
	v_add_f32_e32 v160, v160, v165
	s_waitcnt lgkmcnt(0)
	v_add_f32_e32 v157, v157, v162
	ds_bpermute_b32 v162, v190, v164
	ds_bpermute_b32 v165, v190, v160
	v_fmac_f32_e32 v156, v26, v168
	v_fmac_f32_e32 v156, v27, v169
	v_fmac_f32_e32 v156, v28, v170
	s_waitcnt lgkmcnt(1)
	v_add_f32_e32 v162, v164, v162
	s_waitcnt lgkmcnt(0)
	v_add_f32_e32 v160, v160, v165
	ds_bpermute_b32 v164, v191, v162
	ds_bpermute_b32 v165, v191, v160
	v_fmac_f32_e32 v156, v29, v171
	v_fmac_f32_e32 v156, v30, v172
	v_fmac_f32_e32 v156, v31, v173
	s_waitcnt lgkmcnt(1)
	v_add_f32_e32 v162, v162, v164
	s_waitcnt lgkmcnt(0)
	v_add_f32_e32 v160, v160, v165
	ds_bpermute_b32 v164, v192, v162
	ds_bpermute_b32 v165, v192, v160
	v_fmac_f32_e32 v156, v32, v174
	v_fmac_f32_e32 v156, v33, v175
	v_fmac_f32_e32 v156, v34, v176
	v_fmac_f32_e32 v156, v35, v177
	s_waitcnt lgkmcnt(1)
	v_add_f32_e32 v162, v162, v164
	s_waitcnt lgkmcnt(0)
	v_add_f32_e32 v165, v160, v165
	v_fmac_f32_e32 v156, v36, v178
	ds_bpermute_b32 v164, v193, v162
	ds_bpermute_b32 v182, v193, v165
	v_fmac_f32_e32 v156, v37, v179
	v_fmac_f32_e32 v156, v38, v180
	v_fmac_f32_e32 v156, v39, v181
	ds_bpermute_b32 v161, v189, v156
	v_fma_f32 v158, v56, v166, 0
	s_waitcnt lgkmcnt(2)
	v_add_f32_e32 v162, v162, v164
	s_waitcnt lgkmcnt(1)
	v_add_f32_e32 v164, v165, v182
	v_fma_f32 v182, v16, v166, 0
	v_fma_f32 v184, v96, v166, 0
	v_fma_f32 v166, v112, v166, 0
	v_fmac_f32_e32 v158, v57, v167
	v_fmac_f32_e32 v182, v17, v167
	v_fmac_f32_e32 v184, v97, v167
	v_fmac_f32_e32 v166, v113, v167
	v_fmac_f32_e32 v158, v58, v168
	v_fmac_f32_e32 v182, v18, v168
	v_fmac_f32_e32 v184, v98, v168
	v_fmac_f32_e32 v166, v114, v168
	v_fmac_f32_e32 v158, v59, v169
	v_fmac_f32_e32 v182, v19, v169
	v_fmac_f32_e32 v184, v99, v169
	v_fmac_f32_e32 v166, v115, v169
	v_fmac_f32_e32 v158, v60, v170
	s_waitcnt lgkmcnt(0)
	v_add_f32_e32 v156, v156, v161
	v_fmac_f32_e32 v182, v20, v170
	v_fmac_f32_e32 v184, v100, v170
	v_fmac_f32_e32 v166, v116, v170
	v_fmac_f32_e32 v158, v61, v171
	ds_bpermute_b32 v161, v190, v156
	v_fmac_f32_e32 v182, v21, v171
	v_fmac_f32_e32 v184, v101, v171
	v_fmac_f32_e32 v166, v117, v171
	v_fmac_f32_e32 v158, v62, v172
	v_fmac_f32_e32 v182, v22, v172
	v_fmac_f32_e32 v184, v102, v172
	v_fmac_f32_e32 v166, v118, v172
	v_fmac_f32_e32 v158, v63, v173
	v_fmac_f32_e32 v182, v23, v173
	v_fmac_f32_e32 v184, v103, v173
	v_fmac_f32_e32 v166, v119, v173
	v_fmac_f32_e32 v158, v64, v174
	v_fmac_f32_e32 v182, v88, v174
	v_fmac_f32_e32 v184, v104, v174
	v_fmac_f32_e32 v166, v120, v174
	v_fmac_f32_e32 v158, v65, v175
	v_fmac_f32_e32 v182, v89, v175
	v_fmac_f32_e32 v184, v105, v175
	v_fmac_f32_e32 v166, v121, v175
	v_fmac_f32_e32 v158, v66, v176
	s_waitcnt lgkmcnt(0)
; __device__ __forceinline__ float wave_sum(float v) {
; #pragma unroll
;     for (int o = 1; o < 64; o <<= 1) v += __shfl_xor(v, o);
;     return v;
; }
; __device__ __forceinline__ void sw_rows(const bf16_t* Bt, int nrows, const float* shift, float* sW, int gw, int NGW, int lane) {
;     ...
;         float v = 0.f;
; #pragma unroll
;         for (int b = 0; b < 8; ++b) { float acc = 0.f;
; #pragma unroll
;             for (int i = 0; i < 16; ++i) acc += sh[b][i] * w[i];
;             acc = wave_sum(acc); v = (lane == b) ? acc : v; }
;         if (lane < 8) sW[(size_t)lane * SW_ROWS + row] = v;
	v_add_f32_e32 v156, v156, v161
	v_fmac_f32_e32 v182, v90, v176
	v_fmac_f32_e32 v184, v106, v176
	v_fmac_f32_e32 v166, v122, v176
	v_fmac_f32_e32 v158, v67, v177
	ds_bpermute_b32 v161, v191, v156
	v_fmac_f32_e32 v182, v91, v177
	v_fmac_f32_e32 v184, v107, v177
	v_fmac_f32_e32 v166, v123, v177
	v_fmac_f32_e32 v158, v68, v178
	v_fmac_f32_e32 v182, v92, v178
	v_fmac_f32_e32 v184, v108, v178
	v_fmac_f32_e32 v166, v124, v178
	v_fmac_f32_e32 v158, v69, v179
	v_fmac_f32_e32 v182, v93, v179
	v_fmac_f32_e32 v184, v109, v179
	v_fmac_f32_e32 v166, v125, v179
	v_fmac_f32_e32 v158, v70, v180
	v_fmac_f32_e32 v182, v94, v180
	v_fmac_f32_e32 v184, v110, v180
	v_fmac_f32_e32 v166, v126, v180
	v_fmac_f32_e32 v158, v71, v181
	v_fmac_f32_e32 v182, v95, v181
	v_fmac_f32_e32 v184, v111, v181
	v_fmac_f32_e32 v166, v127, v181
	ds_bpermute_b32 v163, v189, v158
	s_waitcnt lgkmcnt(1)
	v_add_f32_e32 v156, v156, v161
	ds_bpermute_b32 v183, v189, v182
	ds_bpermute_b32 v185, v189, v184
	ds_bpermute_b32 v167, v189, v166
	ds_bpermute_b32 v161, v192, v156
	s_waitcnt lgkmcnt(4)
	v_add_f32_e32 v163, v158, v163
	s_waitcnt lgkmcnt(3)
	v_add_f32_e32 v168, v182, v183
	s_waitcnt lgkmcnt(2)
	v_add_f32_e32 v170, v184, v185
	s_waitcnt lgkmcnt(1)
	v_add_f32_e32 v166, v166, v167
	s_waitcnt lgkmcnt(0)
	v_add_f32_e32 v156, v156, v161
	ds_bpermute_b32 v161, v190, v163
	ds_bpermute_b32 v169, v190, v168
	ds_bpermute_b32 v171, v190, v170
	ds_bpermute_b32 v167, v190, v166
	ds_bpermute_b32 v158, v193, v156
	s_waitcnt lgkmcnt(4)
	v_add_f32_e32 v161, v163, v161
	s_waitcnt lgkmcnt(3)
	v_add_f32_e32 v168, v168, v169
	s_waitcnt lgkmcnt(2)
	v_add_f32_e32 v170, v170, v171
	s_waitcnt lgkmcnt(1)
	v_add_f32_e32 v166, v166, v167
	ds_bpermute_b32 v163, v191, v161
	ds_bpermute_b32 v169, v191, v168
	ds_bpermute_b32 v171, v191, v170
	ds_bpermute_b32 v167, v191, v166
	ds_bpermute_b32 v159, v193, v157
	s_waitcnt lgkmcnt(4)
	v_add_f32_e32 v161, v161, v163
	s_waitcnt lgkmcnt(3)
	v_add_f32_e32 v168, v168, v169
	s_waitcnt lgkmcnt(2)
	v_add_f32_e32 v170, v170, v171
	s_waitcnt lgkmcnt(1)
	v_add_f32_e32 v166, v166, v167
	ds_bpermute_b32 v163, v192, v161
	ds_bpermute_b32 v169, v192, v168
	ds_bpermute_b32 v171, v192, v170
	ds_bpermute_b32 v167, v192, v166
	v_add_f32_e32 v156, v156, v158
	s_waitcnt lgkmcnt(3)
	v_add_f32_e32 v161, v161, v163
	s_waitcnt lgkmcnt(2)
	v_add_f32_e32 v168, v168, v169
	s_waitcnt lgkmcnt(1)
	v_add_f32_e32 v170, v170, v171
	s_waitcnt lgkmcnt(0)
	v_add_f32_e32 v172, v166, v167
	ds_bpermute_b32 v163, v193, v161
	ds_bpermute_b32 v169, v193, v168
	ds_bpermute_b32 v171, v193, v170
	ds_bpermute_b32 v173, v193, v172
	v_add_f32_e32 v158, v157, v159
	s_waitcnt lgkmcnt(3)
	v_add_f32_e32 v160, v161, v163
	s_waitcnt lgkmcnt(2)
	v_add_f32_e32 v166, v168, v169
	s_waitcnt lgkmcnt(1)
	v_add_f32_e32 v168, v170, v171
	s_waitcnt lgkmcnt(0)
	v_add_f32_e32 v170, v172, v173
	ds_bpermute_b32 v157, v194, v156
	ds_bpermute_b32 v159, v194, v158
	ds_bpermute_b32 v161, v194, v160
	ds_bpermute_b32 v163, v194, v162
	ds_bpermute_b32 v165, v194, v164
	ds_bpermute_b32 v167, v194, v166
	ds_bpermute_b32 v169, v194, v168
	ds_bpermute_b32 v171, v194, v170
	s_and_saveexec_b64 s[78:79], s[22:23]
	s_cbranch_execz .LBB0_81
	s_waitcnt lgkmcnt(7)
	v_add_f32_e32 v156, v156, v157
	s_waitcnt lgkmcnt(6)
	v_add_f32_e32 v158, v158, v159
	v_cndmask_b32_e64 v156, 0, v156, s[0:1]
	s_waitcnt lgkmcnt(5)
	v_add_f32_e32 v160, v160, v161
	v_cndmask_b32_e64 v156, v156, v158, s[16:17]
	s_waitcnt lgkmcnt(4)
	v_add_f32_e32 v162, v162, v163
	v_cndmask_b32_e64 v156, v156, v160, s[14:15]
	s_waitcnt lgkmcnt(3)
	v_add_f32_e32 v164, v164, v165
	v_cndmask_b32_e64 v156, v156, v162, s[12:13]
	s_waitcnt lgkmcnt(2)
	v_add_f32_e32 v166, v166, v167
	v_cndmask_b32_e64 v156, v156, v164, s[10:11]
	s_waitcnt lgkmcnt(1)
	v_add_f32_e32 v168, v168, v169
	v_cndmask_b32_e64 v156, v156, v166, s[8:9]
	s_waitcnt lgkmcnt(0)
	v_add_f32_e32 v170, v170, v171
	v_cndmask_b32_e64 v156, v156, v168, s[6:7]
	v_cndmask_b32_e64 v156, v156, v170, s[4:5]
	global_store_dword v[154:155], v156, off
	s_branch .LBB0_81
; __device__ __forceinline__ void sw_rows(const bf16_t* Bt, int nrows, const float* shift, float* sW, int gw, int NGW, int lane) {
;     ...
;     for (int b = 0; b < 8; ++b)
; #pragma unroll
;         for (int j = 0; j < 2; ++j) { const f32x4 a0 = *(const f32x4*)(shift + (size_t)b * NMOD + j * 512 + 8 * lane), a1 = *(const f32x4*)(shift + (size_t)b * NMOD + j * 512 + 8 * lane + 4);
;             sh[b][8 * j + 0] = a0[0]; sh[b][8 * j + 1] = a0[1]; sh[b][8 * j + 2] = a0[2]; sh[b][8 * j + 3] = a0[3]; sh[b][8 * j + 4] = a1[0]; sh[b][8 * j + 5] = a1[1]; sh[b][8 * j + 6] = a1[2]; sh[b][8 * j + 7] = a1[3]; }
;     for (int row = gw; row < nrows; row += NGW) {
;         const bf16_t* r = Bt + (size_t)row * 1024 + 8 * lane;
;         const u32x4 w0 = *(const u32x4*)r, w1 = *(const u32x4*)(r + 512);
.LBB0_84:
	s_and_b64 vcc, exec, s[18:19]
	s_cbranch_vccnz .LBB0_67
	v_lshl_add_u64 v[120:121], s[74:75], 0, v[132:133]
	s_mov_b64 s[18:19], 0x6000
	s_waitcnt vmcnt(3)
	v_lshl_add_u64 v[12:13], v[120:121], 0, s[18:19]
	s_waitcnt vmcnt(2)
	v_add_co_u32_e32 v8, vcc, 0x6000, v120
	s_mov_b64 s[18:19], 0xf000
	s_nop 0
	v_addc_co_u32_e32 v9, vcc, 0, v121, vcc
	s_waitcnt vmcnt(0)
	v_lshl_add_u64 v[20:21], v[120:121], 0, s[18:19]
	s_mov_b32 s18, 0xf000
	v_add_co_u32_e32 v24, vcc, s18, v120
	s_mov_b64 s[18:19], 0xf800
	v_lshl_add_u64 v[28:29], v[120:121], 0, s[18:19]
	s_mov_b64 s[18:19], 0x18000
	v_addc_co_u32_e32 v25, vcc, 0, v121, vcc
	v_lshl_add_u64 v[36:37], v[120:121], 0, s[18:19]
	s_mov_b32 s18, 0x18000
	v_add_co_u32_e32 v40, vcc, s18, v120
	s_mov_b64 s[18:19], 0x18800
	v_lshl_add_u64 v[44:45], v[120:121], 0, s[18:19]
	s_mov_b64 s[18:19], 0x21000
	v_addc_co_u32_e32 v41, vcc, 0, v121, vcc
	v_lshl_add_u64 v[52:53], v[120:121], 0, s[18:19]
	s_mov_b32 s18, 0x21000
	v_add_co_u32_e32 v56, vcc, s18, v120
	s_mov_b64 s[18:19], 0x21800
	v_lshl_add_u64 v[60:61], v[120:121], 0, s[18:19]
	s_mov_b64 s[18:19], 0x2a000
	v_addc_co_u32_e32 v57, vcc, 0, v121, vcc
	v_lshl_add_u64 v[68:69], v[120:121], 0, s[18:19]
	s_mov_b32 s18, 0x2a000
	v_add_co_u32_e32 v72, vcc, s18, v120
	s_mov_b64 s[18:19], 0x2a800
	v_lshl_add_u64 v[76:77], v[120:121], 0, s[18:19]
	s_mov_b64 s[18:19], 0x33000
	v_addc_co_u32_e32 v73, vcc, 0, v121, vcc
	v_lshl_add_u64 v[84:85], v[120:121], 0, s[18:19]
	s_mov_b32 s18, 0x33000
	v_add_co_u32_e32 v88, vcc, s18, v120
	s_mov_b64 s[18:19], 0x33800
	v_lshl_add_u64 v[92:93], v[120:121], 0, s[18:19]
	s_mov_b64 s[18:19], 0x3c000
	v_addc_co_u32_e32 v89, vcc, 0, v121, vcc
	v_lshl_add_u64 v[100:101], v[120:121], 0, s[18:19]
	s_mov_b32 s18, 0x3c000
	v_add_co_u32_e32 v104, vcc, s18, v120
	s_mov_b64 s[18:19], 0x3c800
	s_nop 0
	v_addc_co_u32_e32 v105, vcc, 0, v121, vcc
	v_lshl_add_u64 v[108:109], v[120:121], 0, s[18:19]
	s_mov_b32 s18, 0x45000
	global_load_dwordx4 v[0:3], v[12:13], off offset:16
	global_load_dwordx4 v[4:7], v[12:13], off offset:2048
	s_nop 0
	global_load_dwordx4 v[8:11], v[8:9], off
	s_nop 0
	global_load_dwordx4 v[12:15], v[12:13], off offset:2064
	v_add_co_u32_e32 v122, vcc, s18, v120
	v_lshl_add_u64 v[116:117], v[120:121], 0, s[62:63]
	s_nop 0
	v_addc_co_u32_e32 v123, vcc, 0, v121, vcc
	v_lshl_add_u64 v[124:125], v[120:121], 0, s[64:65]
	global_load_dwordx4 v[16:19], v[24:25], off
	s_nop 0
	global_load_dwordx4 v[20:23], v[20:21], off offset:16
	s_nop 0
	global_load_dwordx4 v[24:27], v[24:25], off offset:2048
	s_nop 0
	global_load_dwordx4 v[28:31], v[28:29], off offset:16
	s_nop 0
	global_load_dwordx4 v[32:35], v[40:41], off
	s_nop 0
	global_load_dwordx4 v[36:39], v[36:37], off offset:16
	s_nop 0
	global_load_dwordx4 v[40:43], v[40:41], off offset:2048
	s_nop 0
	global_load_dwordx4 v[44:47], v[44:45], off offset:16
	s_nop 0
	global_load_dwordx4 v[48:51], v[56:57], off
	s_nop 0
	global_load_dwordx4 v[52:55], v[52:53], off offset:16
	s_nop 0
	global_load_dwordx4 v[56:59], v[56:57], off offset:2048
	s_nop 0
	global_load_dwordx4 v[60:63], v[60:61], off offset:16
	s_nop 0
	global_load_dwordx4 v[64:67], v[72:73], off
	s_nop 0
	global_load_dwordx4 v[68:71], v[68:69], off offset:16
	s_nop 0
	global_load_dwordx4 v[72:75], v[72:73], off offset:2048
	s_nop 0
	global_load_dwordx4 v[76:79], v[76:77], off offset:16
	s_nop 0
	global_load_dwordx4 v[80:83], v[88:89], off
	s_nop 0
	global_load_dwordx4 v[84:87], v[84:85], off offset:16
	s_nop 0
	global_load_dwordx4 v[88:91], v[88:89], off offset:2048
	s_nop 0
	global_load_dwordx4 v[92:95], v[92:93], off offset:16
	s_nop 0
	global_load_dwordx4 v[96:99], v[104:105], off
	s_nop 0
	global_load_dwordx4 v[100:103], v[100:101], off offset:16
	s_nop 0
	global_load_dwordx4 v[104:107], v[104:105], off offset:2048
	s_nop 0
	global_load_dwordx4 v[108:111], v[108:109], off offset:16
	s_nop 0
	global_load_dwordx4 v[112:115], v[122:123], off
	s_nop 0
	global_load_dwordx4 v[116:119], v[116:117], off offset:16
	s_nop 0
	global_load_dwordx4 v[120:123], v[122:123], off offset:2048
	s_nop 0
	global_load_dwordx4 v[124:127], v[124:125], off offset:16
	v_mov_b64_e32 v[152:153], v[150:151]
	global_load_dwordx4 v[230:233], v[152:153], off
	global_load_dwordx4 v[234:237], v[152:153], off offset:1024
	s_waitcnt vmcnt(0)
	v_mov_b64_e32 v[154:155], v[148:149]
	s_mov_b32 s37, s36
	s_branch .LBB0_87

; __device__ __forceinline__ void sw_rows(const bf16_t* Bt, int nrows, const float* shift, float* sW, int gw, int NGW, int lane) {
;     ...
;     for (int row = gw; row < nrows; row += NGW) {
;         const bf16_t* r = Bt + (size_t)row * 1024 + 8 * lane;
;         const u32x4 w0 = *(const u32x4*)r, w1 = *(const u32x4*)(r + 512);
;         float w[16];
;         w[0] = bf_lo(w0.x); w[1] = bf_hi(w0.x); w[2] = bf_lo(w0.y); w[3] = bf_hi(w0.y); w[4] = bf_lo(w0.z); w[5] = bf_hi(w0.z); w[6] = bf_lo(w0.w); w[7] = bf_hi(w0.w);
;         w[8] = bf_lo(w1.x); w[9] = bf_hi(w1.x); w[10] = bf_lo(w1.y); w[11] = bf_hi(w1.y); w[12] = bf_lo(w1.z); w[13] = bf_hi(w1.z); w[14] = bf_lo(w1.w); w[15] = bf_hi(w1.w);
;         float v = 0.f;
; #pragma unroll
;         for (int b = 0; b < 8; ++b) { float acc = 0.f;
; #pragma unroll
;             for (int i = 0; i < 16; ++i) acc += sh[b][i] * w[i];
;             acc = wave_sum(acc); v = (lane == b) ? acc : v; }
.LBB0_87:
	s_waitcnt vmcnt(1) lgkmcnt(0)
	v_mov_b32_e32 v156, v230
	v_mov_b32_e32 v157, v231
	v_mov_b32_e32 v158, v232
	v_mov_b32_e32 v159, v233
	v_mov_b32_e32 v160, v234
	v_mov_b32_e32 v161, v235
	v_mov_b32_e32 v162, v236
	v_mov_b32_e32 v163, v237
	v_lshl_add_u64 v[238:239], v[152:153], 0, s[54:55]
	global_load_dwordx4 v[230:233], v[238:239], off
	global_load_dwordx4 v[234:237], v[238:239], off offset:1024
	v_lshlrev_b32_e32 v166, 16, v156
	s_waitcnt lgkmcnt(2)
	v_and_b32_e32 v167, 0xffff0000, v156
	v_lshlrev_b32_e32 v168, 16, v157
	s_waitcnt lgkmcnt(1)
	v_and_b32_e32 v169, 0xffff0000, v157
	v_fma_f32 v157, v16, v166, 0
	v_fmac_f32_e32 v157, v17, v167
	v_fmac_f32_e32 v157, v18, v168
	v_lshlrev_b32_e32 v170, 16, v158
	v_fmac_f32_e32 v157, v19, v169
	s_waitcnt lgkmcnt(0)
	v_and_b32_e32 v171, 0xffff0000, v158
	v_fmac_f32_e32 v157, v20, v170
	v_lshlrev_b32_e32 v172, 16, v159
	v_fmac_f32_e32 v157, v21, v171
	v_and_b32_e32 v173, 0xffff0000, v159
	v_fmac_f32_e32 v157, v22, v172
	v_lshlrev_b32_e32 v174, 16, v160
	v_fmac_f32_e32 v157, v23, v173
	v_and_b32_e32 v175, 0xffff0000, v160
	v_fmac_f32_e32 v157, v24, v174
	v_lshlrev_b32_e32 v176, 16, v161
	v_fmac_f32_e32 v157, v25, v175
	v_and_b32_e32 v177, 0xffff0000, v161
	v_fmac_f32_e32 v157, v26, v176
	v_lshlrev_b32_e32 v178, 16, v162
	v_fmac_f32_e32 v157, v27, v177
	v_and_b32_e32 v179, 0xffff0000, v162
	v_fmac_f32_e32 v157, v28, v178
	v_lshlrev_b32_e32 v180, 16, v163
	v_fmac_f32_e32 v157, v29, v179
	v_and_b32_e32 v181, 0xffff0000, v163
	v_fmac_f32_e32 v157, v30, v180
	v_fmac_f32_e32 v157, v31, v181
	ds_bpermute_b32 v162, v189, v157
	v_fma_f32 v159, v48, v166, 0
	v_fma_f32 v160, v64, v166, 0
	v_fmac_f32_e32 v159, v49, v167
	v_fmac_f32_e32 v160, v65, v167
	v_fmac_f32_e32 v159, v50, v168
	v_fmac_f32_e32 v160, v66, v168
	v_fmac_f32_e32 v159, v51, v169
	v_fmac_f32_e32 v160, v67, v169
	v_fmac_f32_e32 v159, v52, v170
	v_fmac_f32_e32 v160, v68, v170
	s_waitcnt lgkmcnt(0)
	v_add_f32_e32 v157, v157, v162
	v_fmac_f32_e32 v159, v53, v171
	v_fmac_f32_e32 v160, v69, v171
	ds_bpermute_b32 v162, v190, v157
	v_fmac_f32_e32 v159, v54, v172
	v_fmac_f32_e32 v160, v70, v172
	v_fmac_f32_e32 v159, v55, v173
	v_fmac_f32_e32 v160, v71, v173
	v_fmac_f32_e32 v159, v56, v174
	v_fmac_f32_e32 v160, v72, v174
	v_fmac_f32_e32 v159, v57, v175
	v_fmac_f32_e32 v160, v73, v175
	v_fmac_f32_e32 v159, v58, v176
	v_fmac_f32_e32 v160, v74, v176
	s_waitcnt lgkmcnt(0)
	v_add_f32_e32 v157, v157, v162
	v_fmac_f32_e32 v159, v59, v177
	v_fmac_f32_e32 v160, v75, v177
	ds_bpermute_b32 v162, v191, v157
	v_fmac_f32_e32 v159, v60, v178
	v_fmac_f32_e32 v160, v76, v178
	v_fmac_f32_e32 v159, v61, v179
	v_fmac_f32_e32 v160, v77, v179
	v_fmac_f32_e32 v159, v62, v180
	v_fmac_f32_e32 v160, v78, v180
	v_fmac_f32_e32 v159, v63, v181
	v_fmac_f32_e32 v160, v79, v181
	ds_bpermute_b32 v164, v189, v159
	s_waitcnt lgkmcnt(1)
	v_add_f32_e32 v157, v157, v162
	ds_bpermute_b32 v165, v189, v160
	ds_bpermute_b32 v162, v192, v157
	v_fma_f32 v156, v8, v166, 0
	s_waitcnt lgkmcnt(2)
	v_add_f32_e32 v164, v159, v164
	v_fmac_f32_e32 v156, v9, v167
	s_waitcnt lgkmcnt(1)
	v_add_f32_e32 v160, v160, v165
	s_waitcnt lgkmcnt(0)
	v_add_f32_e32 v157, v157, v162
	ds_bpermute_b32 v162, v190, v164
	ds_bpermute_b32 v165, v190, v160
	v_fmac_f32_e32 v156, v10, v168
	v_fmac_f32_e32 v156, v11, v169
	v_fmac_f32_e32 v156, v0, v170
	s_waitcnt lgkmcnt(1)
	v_add_f32_e32 v162, v164, v162
	s_waitcnt lgkmcnt(0)
	v_add_f32_e32 v160, v160, v165
	ds_bpermute_b32 v164, v191, v162
	ds_bpermute_b32 v165, v191, v160
	v_fmac_f32_e32 v156, v1, v171
	v_fmac_f32_e32 v156, v2, v172
	v_fmac_f32_e32 v156, v3, v173
	s_waitcnt lgkmcnt(1)
	v_add_f32_e32 v162, v162, v164
	s_waitcnt lgkmcnt(0)
	v_add_f32_e32 v160, v160, v165
	ds_bpermute_b32 v164, v192, v162
	ds_bpermute_b32 v165, v192, v160
	v_fmac_f32_e32 v156, v4, v174
	v_fmac_f32_e32 v156, v5, v175
	v_fmac_f32_e32 v156, v6, v176
	v_fmac_f32_e32 v156, v7, v177
	s_waitcnt lgkmcnt(1)
	v_add_f32_e32 v162, v162, v164
	s_waitcnt lgkmcnt(0)
	v_add_f32_e32 v165, v160, v165
	v_fmac_f32_e32 v156, v12, v178
	ds_bpermute_b32 v164, v193, v162
	ds_bpermute_b32 v182, v193, v165
	v_fmac_f32_e32 v156, v13, v179
	v_fmac_f32_e32 v156, v14, v180
	v_fmac_f32_e32 v156, v15, v181
	ds_bpermute_b32 v161, v189, v156
	v_fma_f32 v158, v32, v166, 0
	s_waitcnt lgkmcnt(2)
	v_add_f32_e32 v162, v162, v164
	s_waitcnt lgkmcnt(1)
	v_add_f32_e32 v164, v165, v182
	v_fma_f32 v182, v80, v166, 0
	v_fma_f32 v184, v96, v166, 0
	v_fma_f32 v166, v112, v166, 0
	v_fmac_f32_e32 v158, v33, v167
	v_fmac_f32_e32 v182, v81, v167
	v_fmac_f32_e32 v184, v97, v167
	v_fmac_f32_e32 v166, v113, v167
	v_fmac_f32_e32 v158, v34, v168
	v_fmac_f32_e32 v182, v82, v168
	v_fmac_f32_e32 v184, v98, v168
	v_fmac_f32_e32 v166, v114, v168
	v_fmac_f32_e32 v158, v35, v169
	v_fmac_f32_e32 v182, v83, v169
	v_fmac_f32_e32 v184, v99, v169
	v_fmac_f32_e32 v166, v115, v169
	v_fmac_f32_e32 v158, v36, v170
	s_waitcnt lgkmcnt(0)
; __device__ __forceinline__ float wave_sum(float v) {
; #pragma unroll
;     for (int o = 1; o < 64; o <<= 1) v += __shfl_xor(v, o);
;     return v;
; }
; __device__ __forceinline__ void sw_rows(const bf16_t* Bt, int nrows, const float* shift, float* sW, int gw, int NGW, int lane) {
;     ...
;         float v = 0.f;
; #pragma unroll
;         for (int b = 0; b < 8; ++b) { float acc = 0.f;
; #pragma unroll
;             for (int i = 0; i < 16; ++i) acc += sh[b][i] * w[i];
;             acc = wave_sum(acc); v = (lane == b) ? acc : v; }
;         if (lane < 8) sW[(size_t)lane * SW_ROWS + row] = v;
	v_add_f32_e32 v156, v156, v161
	v_fmac_f32_e32 v182, v84, v170
	v_fmac_f32_e32 v184, v100, v170
	v_fmac_f32_e32 v166, v116, v170
	v_fmac_f32_e32 v158, v37, v171
	ds_bpermute_b32 v161, v190, v156
	v_fmac_f32_e32 v182, v85, v171
	v_fmac_f32_e32 v184, v101, v171
	v_fmac_f32_e32 v166, v117, v171
	v_fmac_f32_e32 v158, v38, v172
	v_fmac_f32_e32 v182, v86, v172
	v_fmac_f32_e32 v184, v102, v172
	v_fmac_f32_e32 v166, v118, v172
	v_fmac_f32_e32 v158, v39, v173
	v_fmac_f32_e32 v182, v87, v173
	v_fmac_f32_e32 v184, v103, v173
	v_fmac_f32_e32 v166, v119, v173
	v_fmac_f32_e32 v158, v40, v174
	v_fmac_f32_e32 v182, v88, v174
	v_fmac_f32_e32 v184, v104, v174
	v_fmac_f32_e32 v166, v120, v174
	v_fmac_f32_e32 v158, v41, v175
	v_fmac_f32_e32 v182, v89, v175
	v_fmac_f32_e32 v184, v105, v175
	v_fmac_f32_e32 v166, v121, v175
	v_fmac_f32_e32 v158, v42, v176
	s_waitcnt lgkmcnt(0)
	v_add_f32_e32 v156, v156, v161
	v_fmac_f32_e32 v182, v90, v176
	v_fmac_f32_e32 v184, v106, v176
	v_fmac_f32_e32 v166, v122, v176
	v_fmac_f32_e32 v158, v43, v177
	ds_bpermute_b32 v161, v191, v156
	v_fmac_f32_e32 v182, v91, v177
	v_fmac_f32_e32 v184, v107, v177
	v_fmac_f32_e32 v166, v123, v177
	v_fmac_f32_e32 v158, v44, v178
	v_fmac_f32_e32 v182, v92, v178
	v_fmac_f32_e32 v184, v108, v178
	v_fmac_f32_e32 v166, v124, v178
	v_fmac_f32_e32 v158, v45, v179
	v_fmac_f32_e32 v182, v93, v179
	v_fmac_f32_e32 v184, v109, v179
	v_fmac_f32_e32 v166, v125, v179
	v_fmac_f32_e32 v158, v46, v180
	v_fmac_f32_e32 v182, v94, v180
	v_fmac_f32_e32 v184, v110, v180
	v_fmac_f32_e32 v166, v126, v180
	v_fmac_f32_e32 v158, v47, v181
	v_fmac_f32_e32 v182, v95, v181
	v_fmac_f32_e32 v184, v111, v181
	v_fmac_f32_e32 v166, v127, v181
	ds_bpermute_b32 v163, v189, v158
	s_waitcnt lgkmcnt(1)
	v_add_f32_e32 v156, v156, v161
	ds_bpermute_b32 v183, v189, v182
	ds_bpermute_b32 v185, v189, v184
	ds_bpermute_b32 v167, v189, v166
	ds_bpermute_b32 v161, v192, v156
	s_waitcnt lgkmcnt(4)
	v_add_f32_e32 v163, v158, v163
	s_waitcnt lgkmcnt(3)
	v_add_f32_e32 v168, v182, v183
	s_waitcnt lgkmcnt(2)
	v_add_f32_e32 v170, v184, v185
	s_waitcnt lgkmcnt(1)
	v_add_f32_e32 v166, v166, v167
	s_waitcnt lgkmcnt(0)
	v_add_f32_e32 v156, v156, v161
	ds_bpermute_b32 v161, v190, v163
	ds_bpermute_b32 v169, v190, v168
	ds_bpermute_b32 v171, v190, v170
	ds_bpermute_b32 v167, v190, v166
	ds_bpermute_b32 v158, v193, v156
	s_waitcnt lgkmcnt(4)
	v_add_f32_e32 v161, v163, v161
	s_waitcnt lgkmcnt(3)
	v_add_f32_e32 v168, v168, v169
	s_waitcnt lgkmcnt(2)
	v_add_f32_e32 v170, v170, v171
	s_waitcnt lgkmcnt(1)
	v_add_f32_e32 v166, v166, v167
	ds_bpermute_b32 v163, v191, v161
	ds_bpermute_b32 v169, v191, v168
	ds_bpermute_b32 v171, v191, v170
	ds_bpermute_b32 v167, v191, v166
	ds_bpermute_b32 v159, v193, v157
	s_waitcnt lgkmcnt(4)
	v_add_f32_e32 v161, v161, v163
	s_waitcnt lgkmcnt(3)
	v_add_f32_e32 v168, v168, v169
	s_waitcnt lgkmcnt(2)
	v_add_f32_e32 v170, v170, v171
	s_waitcnt lgkmcnt(1)
	v_add_f32_e32 v166, v166, v167
	ds_bpermute_b32 v163, v192, v161
	ds_bpermute_b32 v169, v192, v168
	ds_bpermute_b32 v171, v192, v170
	ds_bpermute_b32 v167, v192, v166
	v_add_f32_e32 v156, v156, v158
	s_waitcnt lgkmcnt(3)
	v_add_f32_e32 v161, v161, v163
	s_waitcnt lgkmcnt(2)
	v_add_f32_e32 v168, v168, v169
	s_waitcnt lgkmcnt(1)
	v_add_f32_e32 v170, v170, v171
	s_waitcnt lgkmcnt(0)
	v_add_f32_e32 v172, v166, v167
	ds_bpermute_b32 v163, v193, v161
	ds_bpermute_b32 v169, v193, v168
	ds_bpermute_b32 v171, v193, v170
	ds_bpermute_b32 v173, v193, v172
	v_add_f32_e32 v158, v157, v159
	s_waitcnt lgkmcnt(3)
	v_add_f32_e32 v160, v161, v163
	s_waitcnt lgkmcnt(2)
	v_add_f32_e32 v166, v168, v169
	s_waitcnt lgkmcnt(1)
	v_add_f32_e32 v168, v170, v171
	s_waitcnt lgkmcnt(0)
	v_add_f32_e32 v170, v172, v173
	ds_bpermute_b32 v157, v194, v156
	ds_bpermute_b32 v159, v194, v158
	ds_bpermute_b32 v161, v194, v160
	ds_bpermute_b32 v163, v194, v162
	ds_bpermute_b32 v165, v194, v164
	ds_bpermute_b32 v167, v194, v166
	ds_bpermute_b32 v169, v194, v168
	ds_bpermute_b32 v171, v194, v170
	s_and_saveexec_b64 s[18:19], s[22:23]
	s_cbranch_execz .LBB0_86
	s_waitcnt lgkmcnt(7)
	v_add_f32_e32 v156, v156, v157
	s_waitcnt lgkmcnt(6)
	v_add_f32_e32 v158, v158, v159
	v_cndmask_b32_e64 v156, 0, v156, s[0:1]
	s_waitcnt lgkmcnt(5)
	v_add_f32_e32 v160, v160, v161
	v_cndmask_b32_e64 v156, v156, v158, s[16:17]
	s_waitcnt lgkmcnt(4)
	v_add_f32_e32 v162, v162, v163
	v_cndmask_b32_e64 v156, v156, v160, s[14:15]
	s_waitcnt lgkmcnt(3)
	v_add_f32_e32 v164, v164, v165
	v_cndmask_b32_e64 v156, v156, v162, s[12:13]
	s_waitcnt lgkmcnt(2)
	v_add_f32_e32 v166, v166, v167
	v_cndmask_b32_e64 v156, v156, v164, s[10:11]
	s_waitcnt lgkmcnt(1)
	v_add_f32_e32 v168, v168, v169
	v_cndmask_b32_e64 v156, v156, v166, s[8:9]
	s_waitcnt lgkmcnt(0)
	v_add_f32_e32 v170, v170, v171
	v_cndmask_b32_e64 v156, v156, v168, s[6:7]
	v_cndmask_b32_e64 v156, v156, v170, s[4:5]
	global_store_dword v[154:155], v156, off
	s_branch .LBB0_86

; #define LAS __attribute__((address_space(3)))
; __device__ __forceinline__ void sb_attn_wave(const bf16_t* __restrict__ P, const bf16_t* __restrict__ KHp, const bf16_t* __restrict__ Vt, bf16_t* __restrict__ mixed, int gw, int NGW, int lane, LAS unsigned char* wl) {
;     ...
;             const bool diag = (k0 + 63 >= q0);
;             const bool p1_dead = diag && ((q0 & 63) == 0);
;             f32x16 p0, p1;
; #pragma unroll
;             for (int r = 0; r < 16; ++r) { p0[r] = 0.f; p1[r] = 0.f; }
; #pragma unroll
;             for (int d0 = 0; d0 < 4; ++d0) { const bf16x8 kf0 = *(const LAS bf16x8*)(kl + kro + d0 * 32); p0 = __builtin_amdgcn_mfma_f32_32x32x16_bf16(kf0, qf[d0], p0, 0, 0, 0); }
;             if (!p1_dead) {
; #pragma unroll
;                 for (int d0 = 0; d0 < 4; ++d0) { const bf16x8 kf1 = *(const LAS bf16x8*)(kl + kro + 32 * SB_PITCH + d0 * 32); p1 = __builtin_amdgcn_mfma_f32_32x32x16_bf16(kf1, qf[d0], p1, 0, 0, 0); }
;             }
.LBB0_412:
	ds_read_b128 v[32:35], v158
	ds_read_b128 v[48:51], v158 offset:32
	s_lshl_b32 s12, s38, 6
	s_or_b32 s4, s12, 63
	s_cmp_ge_u32 s4, s48
	s_cselect_b64 s[4:5], -1, 0
	s_and_b64 s[8:9], s[22:23], s[4:5]
	s_and_b64 vcc, exec, s[8:9]
	v_or_b32_e32 v162, s12, v146
	s_waitcnt lgkmcnt(1)
	v_mfma_f32_32x32x16_bf16 v[32:47], v[32:35], v[64:67], 0
	s_waitcnt lgkmcnt(0)
	v_mfma_f32_32x32x16_bf16 v[32:47], v[48:51], v[68:71], v[32:47]
	ds_read_b128 v[48:51], v158 offset:64
	s_waitcnt lgkmcnt(0)
	v_mfma_f32_32x32x16_bf16 v[32:47], v[48:51], v[72:75], v[32:47]
	ds_read_b128 v[48:51], v158 offset:96
	s_waitcnt lgkmcnt(0)
	v_mfma_f32_32x32x16_bf16 v[32:47], v[48:51], v[76:79], v[32:47]
	s_cbranch_vccnz .LBB0_414
	ds_read_b128 v[48:51], v158 offset:4608
	ds_read_b128 v[164:167], v158 offset:4640
	v_or_b32_e32 v163, 48, v162
	v_cmp_lt_u32_e32 vcc, v163, v160
	s_waitcnt lgkmcnt(1)
	v_mfma_f32_32x32x16_bf16 v[48:63], v[48:51], v[64:67], 0
	s_waitcnt lgkmcnt(0)
	v_mfma_f32_32x32x16_bf16 v[48:63], v[164:167], v[68:71], v[48:63]
	ds_read_b128 v[164:167], v158 offset:4672
	s_waitcnt lgkmcnt(0)
	v_mfma_f32_32x32x16_bf16 v[48:63], v[164:167], v[72:75], v[48:63]
	ds_read_b128 v[164:167], v158 offset:4704
	s_waitcnt lgkmcnt(0)
	v_mfma_f32_32x32x16_bf16 v[48:63], v[164:167], v[76:79], v[48:63]
	s_cmp_eq_u64 s[4:5], 0
	s_cbranch_scc1 .Lsb_p1_nomask
	s_nop 11
	v_exp_f32_e32 v56, v56
	v_exp_f32_e32 v57, v57
	v_exp_f32_e32 v58, v58
	v_exp_f32_e32 v59, v59
	v_add_f32_e32 v56, 1.0, v56
	v_rcp_f32_e32 v56, v56
	v_add_f32_e32 v57, 1.0, v57
	v_rcp_f32_e32 v57, v57
	v_add_f32_e32 v58, 1.0, v58
	v_sub_f32_e32 v164, 1.0, v56
	v_cndmask_b32_e32 v163, 1.0, v56, vcc
	v_cndmask_b32_e32 v165, 0, v164, vcc
	v_cndmask_b32_e64 v166, v56, v163, s[4:5]
	v_cndmask_b32_e64 v56, v164, v165, s[4:5]
	v_or_b32_e32 v164, 49, v162
	v_cmp_lt_u32_e32 vcc, v164, v160
	v_rcp_f32_e32 v58, v58
	v_sub_f32_e32 v163, 1.0, v57
	v_cndmask_b32_e32 v164, 1.0, v57, vcc
	v_exp_f32_e32 v60, v60
	v_cndmask_b32_e32 v165, 0, v163, vcc
	v_cndmask_b32_e64 v57, v57, v164, s[4:5]
	v_add_f32_e32 v59, 1.0, v59
	v_cndmask_b32_e64 v163, v163, v165, s[4:5]
	v_mul_f32_e32 v165, v166, v57
	v_or_b32_e32 v166, 50, v162
	v_rcp_f32_e32 v59, v59
	v_sub_f32_e32 v164, 1.0, v58
	v_cmp_lt_u32_e32 vcc, v166, v160
	v_exp_f32_e32 v61, v61
	v_add_f32_e32 v60, 1.0, v60
	v_cndmask_b32_e32 v166, 1.0, v58, vcc
	v_cndmask_b32_e32 v167, 0, v164, vcc
	v_cndmask_b32_e64 v58, v58, v166, s[4:5]
	v_cndmask_b32_e64 v164, v164, v167, s[4:5]
	v_or_b32_e32 v167, 51, v162
	v_rcp_f32_e32 v60, v60
	v_mul_f32_e32 v166, v58, v165
	v_sub_f32_e32 v165, 1.0, v59
	v_cmp_lt_u32_e32 vcc, v167, v160
	v_exp_f32_e32 v62, v62
	v_add_f32_e32 v61, 1.0, v61
	v_cndmask_b32_e32 v167, 1.0, v59, vcc
	v_cndmask_b32_e32 v168, 0, v165, vcc
	v_cndmask_b32_e64 v59, v59, v167, s[4:5]
	v_cndmask_b32_e64 v165, v165, v168, s[4:5]
	v_or_b32_e32 v168, 52, v162
	v_rcp_f32_e32 v61, v61
	v_mul_f32_e32 v167, v59, v166
	v_sub_f32_e32 v166, 1.0, v60
	v_cmp_lt_u32_e32 vcc, v168, v160
	v_add_f32_e32 v62, 1.0, v62
	v_exp_f32_e32 v63, v63
	v_cndmask_b32_e32 v168, 1.0, v60, vcc
	v_cndmask_b32_e32 v169, 0, v166, vcc
	v_cndmask_b32_e64 v60, v60, v168, s[4:5]
	v_cndmask_b32_e64 v166, v166, v169, s[4:5]
	v_or_b32_e32 v169, 53, v162
	v_rcp_f32_e32 v62, v62
	v_mul_f32_e32 v168, v60, v167
	v_sub_f32_e32 v167, 1.0, v61
	v_cmp_lt_u32_e32 vcc, v169, v160
	v_exp_f32_e32 v48, v48
	v_add_f32_e32 v63, 1.0, v63
	v_cndmask_b32_e32 v169, 1.0, v61, vcc
	v_cndmask_b32_e32 v170, 0, v167, vcc
	v_cndmask_b32_e64 v61, v61, v169, s[4:5]
	v_cndmask_b32_e64 v167, v167, v170, s[4:5]
	v_or_b32_e32 v170, 54, v162
	v_mul_f32_e32 v169, v61, v168
	v_sub_f32_e32 v168, 1.0, v62
	v_cmp_lt_u32_e32 vcc, v170, v160
	v_rcp_f32_e32 v63, v63
	v_add_f32_e32 v48, 1.0, v48
	v_cndmask_b32_e32 v171, 0, v168, vcc
	v_cndmask_b32_e64 v168, v168, v171, s[4:5]
	v_or_b32_e32 v171, 55, v162
	v_exp_f32_e32 v49, v49
	v_cndmask_b32_e32 v170, 1.0, v62, vcc
	v_cmp_lt_u32_e32 vcc, v171, v160
	v_rcp_f32_e32 v48, v48
	v_cndmask_b32_e64 v62, v62, v170, s[4:5]
	v_cndmask_b32_e32 v171, 1.0, v63, vcc
	v_mul_f32_e32 v170, v62, v169
	v_sub_f32_e32 v169, 1.0, v63
	v_cndmask_b32_e64 v63, v63, v171, s[4:5]
	v_exp_f32_e32 v50, v50
	v_cndmask_b32_e32 v172, 0, v169, vcc
	v_mul_f32_e32 v171, v63, v170
	v_or_b32_e32 v170, 32, v162
	v_add_f32_e32 v49, 1.0, v49
	v_cndmask_b32_e64 v169, v169, v172, s[4:5]
	v_sub_f32_e32 v172, 1.0, v48
	v_cmp_lt_u32_e32 vcc, v170, v160
	v_rcp_f32_e32 v49, v49
	v_add_f32_e32 v50, 1.0, v50
	v_cndmask_b32_e32 v170, 1.0, v48, vcc
	v_cndmask_b32_e32 v173, 0, v172, vcc
	v_cndmask_b32_e64 v174, v48, v170, s[4:5]
	v_cndmask_b32_e64 v48, v172, v173, s[4:5]
	v_or_b32_e32 v172, 33, v162
	v_exp_f32_e32 v51, v51
	v_cmp_lt_u32_e32 vcc, v172, v160
	v_rcp_f32_e32 v50, v50
	v_sub_f32_e32 v170, 1.0, v49
	v_cndmask_b32_e32 v172, 1.0, v49, vcc
	v_cndmask_b32_e64 v49, v49, v172, s[4:5]
	v_cndmask_b32_e32 v173, 0, v170, vcc
	v_mul_f32_e32 v172, v174, v49
	v_or_b32_e32 v174, 34, v162
	v_add_f32_e32 v51, 1.0, v51
	v_cndmask_b32_e64 v170, v170, v173, s[4:5]
	v_sub_f32_e32 v173, 1.0, v50
	v_cmp_lt_u32_e32 vcc, v174, v160
	v_rcp_f32_e32 v51, v51
	s_nop 0
	v_cndmask_b32_e32 v175, 0, v173, vcc
	v_cndmask_b32_e64 v173, v173, v175, s[4:5]
	v_or_b32_e32 v175, 35, v162
	v_cndmask_b32_e32 v174, 1.0, v50, vcc
	v_cmp_lt_u32_e32 vcc, v175, v160
	v_cndmask_b32_e64 v174, v50, v174, s[4:5]
	v_mul_f32_e32 v50, v174, v172
	v_cndmask_b32_e32 v175, 1.0, v51, vcc
	v_sub_f32_e32 v172, 1.0, v51
	v_cndmask_b32_e64 v175, v51, v175, s[4:5]
	v_exp_f32_e32 v51, v52
	v_cndmask_b32_e32 v176, 0, v172, vcc
	v_cndmask_b32_e64 v172, v172, v176, s[4:5]
	v_or_b32_e32 v176, 36, v162
; __device__ __forceinline__ void sb_attn_wave(const bf16_t* __restrict__ P, const bf16_t* __restrict__ KHp, const bf16_t* __restrict__ Vt, bf16_t* __restrict__ mixed, int gw, int NGW, int lane, LAS unsigned char* wl) {
;     ...
;             float cmid = carry;
;             if (!p1_dead) SB_HALF(p1, 3, 2, carry, cmid);
;             const bool done_mid = __all(cmid < 5.421010862427522e-20f);
;             if (!done_mid) SB_HALF(p0, 1, 0, cmid, carry); else carry = cmid;
	v_add_f32_e32 v51, 1.0, v51
	v_rcp_f32_e32 v51, v51
	v_cmp_lt_u32_e32 vcc, v176, v160
	v_mul_f32_e32 v50, v175, v50
	v_sub_f32_e32 v52, 1.0, v51
	v_cndmask_b32_e32 v176, 1.0, v51, vcc
	v_cndmask_b32_e64 v176, v51, v176, s[4:5]
	v_exp_f32_e32 v51, v53
	v_or_b32_e32 v53, 37, v162
	v_cndmask_b32_e32 v177, 0, v52, vcc
	v_cmp_lt_u32_e32 vcc, v53, v160
	v_add_f32_e32 v51, 1.0, v51
	v_rcp_f32_e32 v51, v51
	v_cndmask_b32_e64 v177, v52, v177, s[4:5]
	v_mul_f32_e32 v50, v176, v50
	v_cndmask_b32_e32 v53, 1.0, v51, vcc
	v_sub_f32_e32 v52, 1.0, v51
	v_cndmask_b32_e64 v179, v51, v53, s[4:5]
	v_exp_f32_e32 v51, v54
	v_or_b32_e32 v53, 38, v162
	v_cndmask_b32_e32 v178, 0, v52, vcc
	v_cmp_lt_u32_e32 vcc, v53, v160
	v_add_f32_e32 v51, 1.0, v51
	v_rcp_f32_e32 v51, v51
	v_cndmask_b32_e64 v178, v52, v178, s[4:5]
	v_mul_f32_e32 v50, v179, v50
	v_cndmask_b32_e32 v53, 1.0, v51, vcc
	v_sub_f32_e32 v52, 1.0, v51
	v_cndmask_b32_e64 v180, v51, v53, s[4:5]
	v_exp_f32_e32 v51, v55
	v_or_b32_e32 v53, 39, v162
	v_cndmask_b32_e32 v54, 0, v52, vcc
	v_cmp_lt_u32_e32 vcc, v53, v160
	v_add_f32_e32 v51, 1.0, v51
	v_rcp_f32_e32 v51, v51
	v_mul_f32_e32 v50, v180, v50
	v_cndmask_b32_e64 v181, v52, v54, s[4:5]
	v_cndmask_b32_e32 v53, 1.0, v51, vcc
	v_cndmask_b32_e64 v182, v51, v53, s[4:5]
	v_mul_f32_e32 v50, v182, v50
	v_sub_f32_e32 v52, 1.0, v51
	ds_bpermute_b32 v51, v156, v171
	ds_bpermute_b32 v184, v156, v50
	v_cndmask_b32_e32 v54, 0, v52, vcc
	v_cndmask_b32_e64 v183, v52, v54, s[4:5]
	s_waitcnt lgkmcnt(1)
	v_mul_f32_e32 v52, v171, v51
	s_waitcnt lgkmcnt(0)
	v_mul_f32_e32 v185, v50, v184
	v_cndmask_b32_e64 v50, 1.0, v51, s[6:7]
	v_mul_f32_e32 v50, v161, v50
	v_mul_f32_e32 v53, v50, v169
	v_mul_f32_e32 v50, v50, v63
	v_mul_f32_e32 v54, v50, v168
	v_mul_f32_e32 v50, v62, v50
	v_mul_f32_e32 v171, v161, v52
	v_mul_f32_e32 v52, v167, v50
	v_mul_f32_e32 v50, v61, v50
	v_mul_f32_e32 v55, v166, v50
	v_mul_f32_e32 v50, v60, v50
	v_mul_f32_e32 v51, v165, v50
	v_mul_f32_e32 v50, v59, v50
	v_mul_f32_e32 v59, v164, v50
	v_mul_f32_e32 v50, v58, v50
	v_mul_f32_e32 v58, v163, v50
	v_mul_f32_e32 v50, v57, v50
	v_mul_f32_e32 v50, v56, v50
	v_cvt_pk_bf16_f32 v50, v50, v58
	v_cvt_pk_bf16_f32 v51, v59, v51
	v_cvt_pk_bf16_f32 v52, v55, v52
	v_cvt_pk_bf16_f32 v53, v54, v53
	ds_read_b128 v[54:57], v159 offset:9280
	ds_read_b128 v[58:61], v159 offset:9312
	ds_read_b128 v[164:167], v159 offset:13920
	s_waitcnt lgkmcnt(1)
	v_mfma_f32_32x32x16_bf16 v[16:31], v[58:61], v[50:53], v[16:31]
	v_mul_f32_e32 v161, v185, v171
	s_waitcnt lgkmcnt(0)
	v_mfma_f32_32x32x16_bf16 v[0:15], v[164:167], v[50:53], v[0:15]
	v_cndmask_b32_e64 v50, 1.0, v184, s[6:7]
	v_mul_f32_e32 v50, v50, v171
	v_mul_f32_e32 v51, v183, v50
	v_mul_f32_e32 v50, v182, v50
	v_mul_f32_e32 v52, v181, v50
	v_mul_f32_e32 v50, v180, v50
	v_mul_f32_e32 v53, v178, v50
	v_mul_f32_e32 v50, v179, v50
	v_mul_f32_e32 v58, v177, v50
	v_mul_f32_e32 v50, v176, v50
	v_mul_f32_e32 v59, v172, v50
	v_mul_f32_e32 v50, v175, v50
	v_mul_f32_e32 v60, v173, v50
	v_mul_f32_e32 v50, v174, v50
	v_mul_f32_e32 v49, v49, v50
	v_mul_f32_e32 v61, v170, v50
	v_mul_f32_e32 v48, v48, v49
	v_cvt_pk_bf16_f32 v48, v48, v61
	v_cvt_pk_bf16_f32 v49, v60, v59
	v_cvt_pk_bf16_f32 v50, v58, v53
	ds_read_b128 v[58:61], v159 offset:13888
	v_cvt_pk_bf16_f32 v51, v52, v51
	s_nop 1
	v_mfma_f32_32x32x16_bf16 v[16:31], v[54:57], v[48:51], v[16:31]
	s_waitcnt lgkmcnt(0)
	v_mfma_f32_32x32x16_bf16 v[0:15], v[58:61], v[48:51], v[0:15]
.LBB0_414:
	v_cmp_gt_f32_e32 vcc, s34, v161
	s_cmp_eq_u64 vcc, exec
	s_cselect_b64 vcc, -1, 0
	s_cbranch_vccnz .LBB0_416
	s_cmp_eq_u64 s[4:5], 0
	s_cbranch_scc1 .Lsb_p0_nomask
	s_nop 6
	v_exp_f32_e32 v40, v40
	v_exp_f32_e32 v41, v41
	v_exp_f32_e32 v42, v42
	v_or_b32_e32 v48, 16, v162
	v_add_f32_e32 v40, 1.0, v40
	v_rcp_f32_e32 v40, v40
	v_add_f32_e32 v41, 1.0, v41
	v_cmp_lt_u32_e64 s[8:9], v48, v160
	v_rcp_f32_e32 v41, v41
	v_sub_f32_e32 v49, 1.0, v40
	v_cndmask_b32_e64 v48, 1.0, v40, s[8:9]
	v_cndmask_b32_e64 v50, 0, v49, s[8:9]
	v_exp_f32_e32 v43, v43
	v_cndmask_b32_e64 v51, v40, v48, s[4:5]
	v_cndmask_b32_e64 v40, v49, v50, s[4:5]
	v_or_b32_e32 v49, 17, v162
	v_add_f32_e32 v42, 1.0, v42
	v_cmp_lt_u32_e64 s[8:9], v49, v160
	v_rcp_f32_e32 v42, v42
	v_sub_f32_e32 v48, 1.0, v41
	v_cndmask_b32_e64 v49, 1.0, v41, s[8:9]
	v_exp_f32_e32 v44, v44
	v_cndmask_b32_e64 v50, 0, v48, s[8:9]
	v_cndmask_b32_e64 v41, v41, v49, s[4:5]
	v_add_f32_e32 v43, 1.0, v43
	v_cndmask_b32_e64 v48, v48, v50, s[4:5]
	v_mul_f32_e32 v50, v51, v41
	v_or_b32_e32 v51, 18, v162
	v_rcp_f32_e32 v43, v43
	v_sub_f32_e32 v49, 1.0, v42
	v_cmp_lt_u32_e64 s[8:9], v51, v160
	v_exp_f32_e32 v45, v45
	v_add_f32_e32 v44, 1.0, v44
	v_cndmask_b32_e64 v51, 1.0, v42, s[8:9]
	v_cndmask_b32_e64 v52, 0, v49, s[8:9]
	v_cndmask_b32_e64 v42, v42, v51, s[4:5]
	v_cndmask_b32_e64 v49, v49, v52, s[4:5]
	v_or_b32_e32 v52, 19, v162
	v_rcp_f32_e32 v44, v44
	v_mul_f32_e32 v51, v42, v50
	v_sub_f32_e32 v50, 1.0, v43
	v_cmp_lt_u32_e64 s[8:9], v52, v160
	v_exp_f32_e32 v46, v46
	v_add_f32_e32 v45, 1.0, v45
	v_cndmask_b32_e64 v52, 1.0, v43, s[8:9]
	v_cndmask_b32_e64 v53, 0, v50, s[8:9]
	v_cndmask_b32_e64 v43, v43, v52, s[4:5]
	v_cndmask_b32_e64 v50, v50, v53, s[4:5]
	v_or_b32_e32 v53, 20, v162
	v_rcp_f32_e32 v45, v45
	v_mul_f32_e32 v52, v43, v51
	v_sub_f32_e32 v51, 1.0, v44
	v_cmp_lt_u32_e64 s[8:9], v53, v160
	v_add_f32_e32 v46, 1.0, v46
	v_exp_f32_e32 v47, v47
	v_cndmask_b32_e64 v53, 1.0, v44, s[8:9]
	v_cndmask_b32_e64 v54, 0, v51, s[8:9]
	v_cndmask_b32_e64 v44, v44, v53, s[4:5]
	v_cndmask_b32_e64 v51, v51, v54, s[4:5]
	v_or_b32_e32 v54, 21, v162
	v_rcp_f32_e32 v46, v46
	v_mul_f32_e32 v53, v44, v52
	v_sub_f32_e32 v52, 1.0, v45
; __device__ __forceinline__ void sb_attn_wave(const bf16_t* __restrict__ P, const bf16_t* __restrict__ KHp, const bf16_t* __restrict__ Vt, bf16_t* __restrict__ mixed, int gw, int NGW, int lane, LAS unsigned char* wl) {
;     ...
;             if (!done_mid) SB_HALF(p0, 1, 0, cmid, carry); else carry = cmid;
	v_cmp_lt_u32_e64 s[8:9], v54, v160
	v_exp_f32_e32 v32, v32
	v_add_f32_e32 v47, 1.0, v47
	v_cndmask_b32_e64 v54, 1.0, v45, s[8:9]
	v_cndmask_b32_e64 v55, 0, v52, s[8:9]
	v_cndmask_b32_e64 v45, v45, v54, s[4:5]
	v_cndmask_b32_e64 v52, v52, v55, s[4:5]
	v_or_b32_e32 v55, 22, v162
	v_mul_f32_e32 v54, v45, v53
	v_sub_f32_e32 v53, 1.0, v46
	v_cmp_lt_u32_e64 s[8:9], v55, v160
	v_rcp_f32_e32 v47, v47
	v_exp_f32_e32 v33, v33
	v_cndmask_b32_e64 v56, 0, v53, s[8:9]
	v_add_f32_e32 v32, 1.0, v32
	v_cndmask_b32_e64 v53, v53, v56, s[4:5]
	v_or_b32_e32 v56, 23, v162
	v_rcp_f32_e32 v32, v32
	v_cndmask_b32_e64 v55, 1.0, v46, s[8:9]
	v_cmp_lt_u32_e64 s[8:9], v56, v160
	v_exp_f32_e32 v34, v34
	v_cndmask_b32_e64 v46, v46, v55, s[4:5]
	v_cndmask_b32_e64 v56, 1.0, v47, s[8:9]
	v_add_f32_e32 v33, 1.0, v33
	v_mul_f32_e32 v55, v46, v54
	v_sub_f32_e32 v54, 1.0, v47
	v_cndmask_b32_e64 v47, v47, v56, s[4:5]
	v_rcp_f32_e32 v33, v33
	v_cndmask_b32_e64 v57, 0, v54, s[8:9]
	v_mul_f32_e32 v56, v47, v55
	v_sub_f32_e32 v55, 1.0, v32
	v_cmp_lt_u32_e64 s[8:9], v162, v160
	v_cndmask_b32_e64 v54, v54, v57, s[4:5]
	v_add_f32_e32 v34, 1.0, v34
	v_cndmask_b32_e64 v57, 1.0, v32, s[8:9]
	v_cndmask_b32_e64 v58, 0, v55, s[8:9]
	v_exp_f32_e32 v35, v35
	v_cndmask_b32_e64 v57, v32, v57, s[4:5]
	v_cndmask_b32_e64 v32, v55, v58, s[4:5]
	v_or_b32_e32 v58, 1, v162
	v_rcp_f32_e32 v34, v34
	v_sub_f32_e32 v55, 1.0, v33
	v_cmp_lt_u32_e64 s[8:9], v58, v160
	v_add_f32_e32 v35, 1.0, v35
	v_rcp_f32_e32 v35, v35
	v_cndmask_b32_e64 v59, 0, v55, s[8:9]
	v_cndmask_b32_e64 v58, 1.0, v33, s[8:9]
	v_cndmask_b32_e64 v55, v55, v59, s[4:5]
	v_or_b32_e32 v59, 2, v162
	v_cndmask_b32_e64 v33, v33, v58, s[4:5]
	v_sub_f32_e32 v58, 1.0, v34
	v_cmp_lt_u32_e64 s[8:9], v59, v160
	v_mul_f32_e32 v57, v57, v33
	s_nop 0
	v_cndmask_b32_e64 v60, 0, v58, s[8:9]
	v_cndmask_b32_e64 v58, v58, v60, s[4:5]
	v_or_b32_e32 v60, 3, v162
	v_cndmask_b32_e64 v59, 1.0, v34, s[8:9]
	v_cmp_lt_u32_e64 s[8:9], v60, v160
	v_cndmask_b32_e64 v59, v34, v59, s[4:5]
	v_mul_f32_e32 v34, v59, v57
	v_cndmask_b32_e64 v60, 1.0, v35, s[8:9]
	v_sub_f32_e32 v57, 1.0, v35
	v_cndmask_b32_e64 v60, v35, v60, s[4:5]
	v_exp_f32_e32 v35, v36
	v_cndmask_b32_e64 v61, 0, v57, s[8:9]
	v_cndmask_b32_e64 v57, v57, v61, s[4:5]
	v_or_b32_e32 v61, 4, v162
	v_add_f32_e32 v35, 1.0, v35
	v_rcp_f32_e32 v35, v35
	v_cmp_lt_u32_e64 s[8:9], v61, v160
	v_mul_f32_e32 v34, v60, v34
	v_sub_f32_e32 v36, 1.0, v35
	v_cndmask_b32_e64 v61, 1.0, v35, s[8:9]
	v_cndmask_b32_e64 v61, v35, v61, s[4:5]
	v_exp_f32_e32 v35, v37
	v_or_b32_e32 v37, 5, v162
	v_cndmask_b32_e64 v62, 0, v36, s[8:9]
	v_cmp_lt_u32_e64 s[8:9], v37, v160
	v_add_f32_e32 v35, 1.0, v35
	v_rcp_f32_e32 v35, v35
	v_cndmask_b32_e64 v62, v36, v62, s[4:5]
	v_mul_f32_e32 v34, v61, v34
	v_cndmask_b32_e64 v37, 1.0, v35, s[8:9]
	v_sub_f32_e32 v36, 1.0, v35
	v_cndmask_b32_e64 v163, v35, v37, s[4:5]
	v_exp_f32_e32 v35, v38
	v_or_b32_e32 v37, 6, v162
	v_cndmask_b32_e64 v63, 0, v36, s[8:9]
	v_cmp_lt_u32_e64 s[8:9], v37, v160
	v_add_f32_e32 v35, 1.0, v35
	v_rcp_f32_e32 v35, v35
	v_cndmask_b32_e64 v63, v36, v63, s[4:5]
	v_mul_f32_e32 v34, v163, v34
	v_cndmask_b32_e64 v37, 1.0, v35, s[8:9]
	v_sub_f32_e32 v36, 1.0, v35
	v_cndmask_b32_e64 v164, v35, v37, s[4:5]
	v_exp_f32_e32 v35, v39
	v_or_b32_e32 v37, 7, v162
	v_cndmask_b32_e64 v38, 0, v36, s[8:9]
	v_cmp_lt_u32_e64 s[8:9], v37, v160
	v_add_f32_e32 v35, 1.0, v35
	v_rcp_f32_e32 v35, v35
	v_mul_f32_e32 v34, v164, v34
	v_cndmask_b32_e64 v165, v36, v38, s[4:5]
	v_cndmask_b32_e64 v37, 1.0, v35, s[8:9]
	v_cndmask_b32_e64 v162, v35, v37, s[4:5]
	v_mul_f32_e32 v34, v162, v34
	v_sub_f32_e32 v36, 1.0, v35
	ds_bpermute_b32 v35, v156, v56
	ds_bpermute_b32 v167, v156, v34
	v_cndmask_b32_e64 v38, 0, v36, s[8:9]
	v_cndmask_b32_e64 v166, v36, v38, s[4:5]
	s_waitcnt lgkmcnt(1)
	v_mul_f32_e32 v36, v56, v35
	s_waitcnt lgkmcnt(0)
	v_mul_f32_e32 v168, v34, v167
	v_cndmask_b32_e64 v34, 1.0, v35, s[6:7]
	v_mul_f32_e32 v34, v161, v34
	v_mul_f32_e32 v37, v54, v34
	v_mul_f32_e32 v34, v47, v34
	v_mul_f32_e32 v38, v53, v34
	v_mul_f32_e32 v34, v46, v34
	v_mul_f32_e32 v56, v161, v36
	v_mul_f32_e32 v36, v52, v34
	v_mul_f32_e32 v34, v45, v34
	v_mul_f32_e32 v39, v51, v34
	v_mul_f32_e32 v34, v44, v34
	v_mul_f32_e32 v35, v50, v34
	v_mul_f32_e32 v34, v43, v34
	v_mul_f32_e32 v43, v49, v34
	v_mul_f32_e32 v34, v42, v34
	v_mul_f32_e32 v42, v48, v34
	v_mul_f32_e32 v34, v41, v34
	v_mul_f32_e32 v34, v40, v34
	v_cvt_pk_bf16_f32 v34, v34, v42
	v_cvt_pk_bf16_f32 v35, v43, v35
	v_cvt_pk_bf16_f32 v36, v39, v36
	v_cvt_pk_bf16_f32 v37, v38, v37
	ds_read_b128 v[38:41], v159 offset:9216
	ds_read_b128 v[42:45], v159 offset:9248
	ds_read_b128 v[46:49], v159 offset:13856
	s_waitcnt lgkmcnt(1)
	v_mfma_f32_32x32x16_bf16 v[16:31], v[42:45], v[34:37], v[16:31]
	v_mul_f32_e32 v161, v56, v168
	s_waitcnt lgkmcnt(0)
	v_mfma_f32_32x32x16_bf16 v[0:15], v[46:49], v[34:37], v[0:15]
	v_cndmask_b32_e64 v34, 1.0, v167, s[6:7]
	v_mul_f32_e32 v34, v56, v34
	v_mul_f32_e32 v35, v166, v34
	v_mul_f32_e32 v34, v162, v34
	v_mul_f32_e32 v36, v165, v34
	v_mul_f32_e32 v34, v164, v34
	v_mul_f32_e32 v37, v63, v34
	v_mul_f32_e32 v34, v163, v34
	v_mul_f32_e32 v42, v62, v34
	v_mul_f32_e32 v34, v61, v34
	v_mul_f32_e32 v43, v57, v34
	v_mul_f32_e32 v34, v60, v34
	v_mul_f32_e32 v44, v58, v34
	v_mul_f32_e32 v34, v59, v34
	v_mul_f32_e32 v33, v33, v34
	v_mul_f32_e32 v45, v55, v34
	v_mul_f32_e32 v32, v32, v33
	v_cvt_pk_bf16_f32 v32, v32, v45
	v_cvt_pk_bf16_f32 v33, v44, v43
	v_cvt_pk_bf16_f32 v34, v42, v37
	ds_read_b128 v[42:45], v159 offset:13824
	v_cvt_pk_bf16_f32 v35, v36, v35
	s_nop 1
	v_mfma_f32_32x32x16_bf16 v[16:31], v[38:41], v[32:35], v[16:31]
	s_waitcnt lgkmcnt(0)
	v_mfma_f32_32x32x16_bf16 v[0:15], v[42:45], v[32:35], v[0:15]

; __device__ __forceinline__ void sb_attn_wave(const bf16_t* __restrict__ P, const bf16_t* __restrict__ KHp, const bf16_t* __restrict__ Vt, bf16_t* __restrict__ mixed, int gw, int NGW, int lane, LAS unsigned char* wl) {
;     ...
;             float cmid = carry;
;             if (!p1_dead) SB_HALF(p1, 3, 2, carry, cmid);
.Lsb_p1_nomask:
	s_nop 11
	v_exp_f32_e32 v56, v56
	v_exp_f32_e32 v57, v57
	v_exp_f32_e32 v58, v58
	v_exp_f32_e32 v59, v59
	v_add_f32_e32 v56, 1.0, v56
	v_rcp_f32_e32 v56, v56
	v_add_f32_e32 v57, 1.0, v57
	v_rcp_f32_e32 v57, v57
	v_add_f32_e32 v58, 1.0, v58
	v_sub_f32_e32 v164, 1.0, v56
	v_mov_b32_e32 v166, v56
	v_mov_b32_e32 v56, v164
	v_rcp_f32_e32 v58, v58
	v_sub_f32_e32 v163, 1.0, v57
	v_exp_f32_e32 v60, v60
	v_add_f32_e32 v59, 1.0, v59
	v_mul_f32_e32 v165, v166, v57
	v_rcp_f32_e32 v59, v59
	v_sub_f32_e32 v164, 1.0, v58
	v_exp_f32_e32 v61, v61
	v_add_f32_e32 v60, 1.0, v60
	v_rcp_f32_e32 v60, v60
	v_mul_f32_e32 v166, v58, v165
	v_sub_f32_e32 v165, 1.0, v59
	v_exp_f32_e32 v62, v62
	v_add_f32_e32 v61, 1.0, v61
	v_rcp_f32_e32 v61, v61
	v_mul_f32_e32 v167, v59, v166
	v_sub_f32_e32 v166, 1.0, v60
	v_add_f32_e32 v62, 1.0, v62
	v_exp_f32_e32 v63, v63
	v_rcp_f32_e32 v62, v62
	v_mul_f32_e32 v168, v60, v167
	v_sub_f32_e32 v167, 1.0, v61
	v_exp_f32_e32 v48, v48
	v_add_f32_e32 v63, 1.0, v63
	v_mul_f32_e32 v169, v61, v168
	v_sub_f32_e32 v168, 1.0, v62
	v_rcp_f32_e32 v63, v63
	v_add_f32_e32 v48, 1.0, v48
	v_exp_f32_e32 v49, v49
	v_rcp_f32_e32 v48, v48
	v_mul_f32_e32 v170, v62, v169
	v_sub_f32_e32 v169, 1.0, v63
	v_exp_f32_e32 v50, v50
	v_mul_f32_e32 v171, v63, v170
	v_add_f32_e32 v49, 1.0, v49
	v_sub_f32_e32 v172, 1.0, v48
	v_rcp_f32_e32 v49, v49
	v_add_f32_e32 v50, 1.0, v50
	v_mov_b32_e32 v174, v48
	v_mov_b32_e32 v48, v172
	v_exp_f32_e32 v51, v51
	v_rcp_f32_e32 v50, v50
	v_sub_f32_e32 v170, 1.0, v49
	v_mul_f32_e32 v172, v174, v49
	v_add_f32_e32 v51, 1.0, v51
	v_sub_f32_e32 v173, 1.0, v50
	v_rcp_f32_e32 v51, v51
	s_nop 0
	v_mov_b32_e32 v174, v50
	v_mul_f32_e32 v50, v174, v172
	v_sub_f32_e32 v172, 1.0, v51
	v_mov_b32_e32 v175, v51
	v_exp_f32_e32 v51, v52
	s_nop 0
	v_add_f32_e32 v51, 1.0, v51
	v_rcp_f32_e32 v51, v51
	v_mul_f32_e32 v50, v175, v50
	v_sub_f32_e32 v52, 1.0, v51
	v_mov_b32_e32 v176, v51
	v_exp_f32_e32 v51, v53
	s_nop 0
	v_add_f32_e32 v51, 1.0, v51
	v_rcp_f32_e32 v51, v51
	v_mov_b32_e32 v177, v52
	v_mul_f32_e32 v50, v176, v50
	v_sub_f32_e32 v52, 1.0, v51
	v_mov_b32_e32 v179, v51
	v_exp_f32_e32 v51, v54
	s_nop 0
	v_add_f32_e32 v51, 1.0, v51
	v_rcp_f32_e32 v51, v51
	v_mov_b32_e32 v178, v52
	v_mul_f32_e32 v50, v179, v50
	v_sub_f32_e32 v52, 1.0, v51
	v_mov_b32_e32 v180, v51
	v_exp_f32_e32 v51, v55
	s_nop 0
	v_add_f32_e32 v51, 1.0, v51
	v_rcp_f32_e32 v51, v51
	v_mul_f32_e32 v50, v180, v50
	v_mov_b32_e32 v181, v52
	v_mov_b32_e32 v182, v51
	v_mul_f32_e32 v50, v182, v50
	v_sub_f32_e32 v52, 1.0, v51
	ds_bpermute_b32 v51, v156, v171
	ds_bpermute_b32 v184, v156, v50
	v_mov_b32_e32 v183, v52
	s_waitcnt lgkmcnt(1)
	v_mul_f32_e32 v52, v171, v51
	s_waitcnt lgkmcnt(0)
	v_mul_f32_e32 v185, v50, v184
	v_cndmask_b32_e64 v50, 1.0, v51, s[6:7]
	v_mul_f32_e32 v50, v161, v50
	v_mul_f32_e32 v53, v50, v169
	v_mul_f32_e32 v50, v50, v63
	v_mul_f32_e32 v54, v50, v168
	v_mul_f32_e32 v50, v62, v50
	v_mul_f32_e32 v171, v161, v52
	v_mul_f32_e32 v52, v167, v50
	v_mul_f32_e32 v50, v61, v50
	v_mul_f32_e32 v55, v166, v50
	v_mul_f32_e32 v50, v60, v50
	v_mul_f32_e32 v51, v165, v50
	v_mul_f32_e32 v50, v59, v50
	v_mul_f32_e32 v59, v164, v50
	v_mul_f32_e32 v50, v58, v50
	v_mul_f32_e32 v58, v163, v50
	v_mul_f32_e32 v50, v57, v50
	v_mul_f32_e32 v50, v56, v50
	v_cvt_pk_bf16_f32 v50, v50, v58
	v_cvt_pk_bf16_f32 v51, v59, v51
	v_cvt_pk_bf16_f32 v52, v55, v52
	v_cvt_pk_bf16_f32 v53, v54, v53
	ds_read_b128 v[54:57], v159 offset:9280
	ds_read_b128 v[58:61], v159 offset:9312
	ds_read_b128 v[164:167], v159 offset:13920
	s_waitcnt lgkmcnt(1)
	v_mfma_f32_32x32x16_bf16 v[16:31], v[58:61], v[50:53], v[16:31]
	v_mul_f32_e32 v161, v185, v171
	s_waitcnt lgkmcnt(0)
	v_mfma_f32_32x32x16_bf16 v[0:15], v[164:167], v[50:53], v[0:15]
	v_cndmask_b32_e64 v50, 1.0, v184, s[6:7]
	v_mul_f32_e32 v50, v50, v171
	v_mul_f32_e32 v51, v183, v50
	v_mul_f32_e32 v50, v182, v50
	v_mul_f32_e32 v52, v181, v50
	v_mul_f32_e32 v50, v180, v50
	v_mul_f32_e32 v53, v178, v50
	v_mul_f32_e32 v50, v179, v50
	v_mul_f32_e32 v58, v177, v50
	v_mul_f32_e32 v50, v176, v50
	v_mul_f32_e32 v59, v172, v50
	v_mul_f32_e32 v50, v175, v50
	v_mul_f32_e32 v60, v173, v50
	v_mul_f32_e32 v50, v174, v50
	v_mul_f32_e32 v49, v49, v50
	v_mul_f32_e32 v61, v170, v50
	v_mul_f32_e32 v48, v48, v49
	v_cvt_pk_bf16_f32 v48, v48, v61
	v_cvt_pk_bf16_f32 v49, v60, v59
	v_cvt_pk_bf16_f32 v50, v58, v53
	ds_read_b128 v[58:61], v159 offset:13888
	v_cvt_pk_bf16_f32 v51, v52, v51
	s_nop 1
	v_mfma_f32_32x32x16_bf16 v[16:31], v[54:57], v[48:51], v[16:31]
	s_waitcnt lgkmcnt(0)
	v_mfma_f32_32x32x16_bf16 v[0:15], v[58:61], v[48:51], v[0:15]
	s_branch .LBB0_414
; __device__ __forceinline__ void sb_attn_wave(const bf16_t* __restrict__ P, const bf16_t* __restrict__ KHp, const bf16_t* __restrict__ Vt, bf16_t* __restrict__ mixed, int gw, int NGW, int lane, LAS unsigned char* wl) {
;     ...
;             float cmid = carry;
;             if (!p1_dead) SB_HALF(p1, 3, 2, carry, cmid);
;             const bool done_mid = __all(cmid < 5.421010862427522e-20f);
;             if (!done_mid) SB_HALF(p0, 1, 0, cmid, carry); else carry = cmid;
.Lsb_p0_nomask:
	s_nop 6
	v_exp_f32_e32 v40, v40
	v_exp_f32_e32 v41, v41
	v_exp_f32_e32 v42, v42
	v_add_f32_e32 v40, 1.0, v40
	v_rcp_f32_e32 v40, v40
	v_add_f32_e32 v41, 1.0, v41
	v_rcp_f32_e32 v41, v41
	v_sub_f32_e32 v49, 1.0, v40
	v_exp_f32_e32 v43, v43
	v_mov_b32_e32 v51, v40
	v_mov_b32_e32 v40, v49
	v_add_f32_e32 v42, 1.0, v42
	v_rcp_f32_e32 v42, v42
	v_sub_f32_e32 v48, 1.0, v41
	v_exp_f32_e32 v44, v44
	v_add_f32_e32 v43, 1.0, v43
	v_mul_f32_e32 v50, v51, v41
	v_rcp_f32_e32 v43, v43
	v_sub_f32_e32 v49, 1.0, v42
	v_exp_f32_e32 v45, v45
	v_add_f32_e32 v44, 1.0, v44
	v_rcp_f32_e32 v44, v44
	v_mul_f32_e32 v51, v42, v50
	v_sub_f32_e32 v50, 1.0, v43
	v_exp_f32_e32 v46, v46
	v_add_f32_e32 v45, 1.0, v45
	v_rcp_f32_e32 v45, v45
	v_mul_f32_e32 v52, v43, v51
	v_sub_f32_e32 v51, 1.0, v44
	v_add_f32_e32 v46, 1.0, v46
	v_exp_f32_e32 v47, v47
	v_rcp_f32_e32 v46, v46
	v_mul_f32_e32 v53, v44, v52
	v_sub_f32_e32 v52, 1.0, v45
	v_exp_f32_e32 v32, v32
	v_add_f32_e32 v47, 1.0, v47
	v_mul_f32_e32 v54, v45, v53
	v_sub_f32_e32 v53, 1.0, v46
	v_rcp_f32_e32 v47, v47
	v_exp_f32_e32 v33, v33
	v_add_f32_e32 v32, 1.0, v32
	v_rcp_f32_e32 v32, v32
	v_exp_f32_e32 v34, v34
	v_add_f32_e32 v33, 1.0, v33
	v_mul_f32_e32 v55, v46, v54
	v_sub_f32_e32 v54, 1.0, v47
	v_rcp_f32_e32 v33, v33
	v_mul_f32_e32 v56, v47, v55
	v_sub_f32_e32 v55, 1.0, v32
	v_add_f32_e32 v34, 1.0, v34
	v_exp_f32_e32 v35, v35
	v_mov_b32_e32 v57, v32
	v_mov_b32_e32 v32, v55
	v_rcp_f32_e32 v34, v34
	v_sub_f32_e32 v55, 1.0, v33
	v_add_f32_e32 v35, 1.0, v35
	v_rcp_f32_e32 v35, v35
	v_sub_f32_e32 v58, 1.0, v34
	v_mul_f32_e32 v57, v57, v33
	s_nop 0
	v_mov_b32_e32 v59, v34
	v_mul_f32_e32 v34, v59, v57
	v_sub_f32_e32 v57, 1.0, v35
	v_mov_b32_e32 v60, v35
	v_exp_f32_e32 v35, v36
	s_nop 0
	v_add_f32_e32 v35, 1.0, v35
	v_rcp_f32_e32 v35, v35
	v_mul_f32_e32 v34, v60, v34
	v_sub_f32_e32 v36, 1.0, v35
	v_mov_b32_e32 v61, v35
	v_exp_f32_e32 v35, v37
	s_nop 0
	v_add_f32_e32 v35, 1.0, v35
	v_rcp_f32_e32 v35, v35
	v_mov_b32_e32 v62, v36
	v_mul_f32_e32 v34, v61, v34
	v_sub_f32_e32 v36, 1.0, v35
	v_mov_b32_e32 v163, v35
	v_exp_f32_e32 v35, v38
	s_nop 0
	v_add_f32_e32 v35, 1.0, v35
	v_rcp_f32_e32 v35, v35
	v_mov_b32_e32 v63, v36
	v_mul_f32_e32 v34, v163, v34
	v_sub_f32_e32 v36, 1.0, v35
	v_mov_b32_e32 v164, v35
	v_exp_f32_e32 v35, v39
	s_nop 0
	v_add_f32_e32 v35, 1.0, v35
	v_rcp_f32_e32 v35, v35
	v_mul_f32_e32 v34, v164, v34
	v_mov_b32_e32 v165, v36
	v_mov_b32_e32 v162, v35
	v_mul_f32_e32 v34, v162, v34
	v_sub_f32_e32 v36, 1.0, v35
	ds_bpermute_b32 v35, v156, v56
	ds_bpermute_b32 v167, v156, v34
	v_mov_b32_e32 v166, v36
	s_waitcnt lgkmcnt(1)
	v_mul_f32_e32 v36, v56, v35
	s_waitcnt lgkmcnt(0)
	v_mul_f32_e32 v168, v34, v167
	v_cndmask_b32_e64 v34, 1.0, v35, s[6:7]
	v_mul_f32_e32 v34, v161, v34
	v_mul_f32_e32 v37, v54, v34
	v_mul_f32_e32 v34, v47, v34
	v_mul_f32_e32 v38, v53, v34
	v_mul_f32_e32 v34, v46, v34
	v_mul_f32_e32 v56, v161, v36
	v_mul_f32_e32 v36, v52, v34
	v_mul_f32_e32 v34, v45, v34
	v_mul_f32_e32 v39, v51, v34
	v_mul_f32_e32 v34, v44, v34
	v_mul_f32_e32 v35, v50, v34
	v_mul_f32_e32 v34, v43, v34
	v_mul_f32_e32 v43, v49, v34
	v_mul_f32_e32 v34, v42, v34
	v_mul_f32_e32 v42, v48, v34
	v_mul_f32_e32 v34, v41, v34
	v_mul_f32_e32 v34, v40, v34
	v_cvt_pk_bf16_f32 v34, v34, v42
	v_cvt_pk_bf16_f32 v35, v43, v35
	v_cvt_pk_bf16_f32 v36, v39, v36
	v_cvt_pk_bf16_f32 v37, v38, v37
	ds_read_b128 v[38:41], v159 offset:9216
	ds_read_b128 v[42:45], v159 offset:9248
	ds_read_b128 v[46:49], v159 offset:13856
	s_waitcnt lgkmcnt(1)
	v_mfma_f32_32x32x16_bf16 v[16:31], v[42:45], v[34:37], v[16:31]
	v_mul_f32_e32 v161, v56, v168
	s_waitcnt lgkmcnt(0)
	v_mfma_f32_32x32x16_bf16 v[0:15], v[46:49], v[34:37], v[0:15]
	v_cndmask_b32_e64 v34, 1.0, v167, s[6:7]
	v_mul_f32_e32 v34, v56, v34
	v_mul_f32_e32 v35, v166, v34
	v_mul_f32_e32 v34, v162, v34
	v_mul_f32_e32 v36, v165, v34
	v_mul_f32_e32 v34, v164, v34
	v_mul_f32_e32 v37, v63, v34
	v_mul_f32_e32 v34, v163, v34
	v_mul_f32_e32 v42, v62, v34
	v_mul_f32_e32 v34, v61, v34
	v_mul_f32_e32 v43, v57, v34
	v_mul_f32_e32 v34, v60, v34
	v_mul_f32_e32 v44, v58, v34
	v_mul_f32_e32 v34, v59, v34
	v_mul_f32_e32 v33, v33, v34
	v_mul_f32_e32 v45, v55, v34
	v_mul_f32_e32 v32, v32, v33
	v_cvt_pk_bf16_f32 v32, v32, v45
	v_cvt_pk_bf16_f32 v33, v44, v43
	v_cvt_pk_bf16_f32 v34, v42, v37
	ds_read_b128 v[42:45], v159 offset:13824
	v_cvt_pk_bf16_f32 v35, v36, v35
	s_nop 1
	v_mfma_f32_32x32x16_bf16 v[16:31], v[38:41], v[32:35], v[16:31]
	s_waitcnt lgkmcnt(0)
	v_mfma_f32_32x32x16_bf16 v[0:15], v[42:45], v[32:35], v[0:15]
	s_branch .LBB0_416
